# coalesced epilogue stores: Mlp1 H + EpiRes AX via ds_bpermute lane transpose, EpiRes f32 residual stores via per-wave LDS transpose (static LDS +16KB)
# speedup vs baseline: 1.0275x; 1.0204x over previous
; #define LAS __attribute__((address_space(3)))
;     __device__ __forceinline__ void operator()(const f32x4 (&acc)[2][2][4][2], const Unit& u, int wr, int wc, int fr, int fq) const {
;         const int b = u.pm >> 3, col0 = u.pn * 256 + wc * 32 + 8 * fq;
;         { const int t = (wr * 4 + wc) * 64 + fq * 16 + fr;
;           if (t < 64) ((LAS f32x4*)gl)[t] = *(const f32x4*)(gate + (size_t)b * gate_ld + u.pn * 256 + 4 * t);
;           else if (t < 128 && gmn) ((LAS f32x4*)gl)[t] = *(const f32x4*)(gmn + (size_t)b * DM + u.pn * 256 + 4 * (t - 64));
;           asm volatile("s_waitcnt vmcnt(0) lgkmcnt(0)" ::: "memory"); __builtin_amdgcn_s_barrier(); asm volatile("" ::: "memory"); }
.LBB0_212:
	s_mul_i32 s100, s5, 36
	s_add_i32 s100, s100, 0x24000
	s_cmp_eq_u32 s5, 0x1c0
	s_cselect_b32 s100, 0x20c00, s100
	s_lshl_b32 s101, s5, 4
	s_add_i32 s101, s101, 0x21800
	v_lshrrev_b32_e32 v210, 2, v242
	v_and_b32_e32 v246, 3, v242
	v_mul_u32_u24_e32 v210, 0x90, v210
	v_lshl_add_u32 v210, v246, 4, v210
	v_add_u32_e32 v210, s100, v210
	v_mul_u32_u24_e32 v208, 0x90, v211
	v_lshl_add_u32 v208, v207, 5, v208
	v_add_u32_e32 v208, s100, v208
	v_lshrrev_b32_e32 v252, 2, v242
	v_sub_u32_e32 v252, v252, v211
	v_lshlrev_b32_e32 v252, 12, v252
	v_lshl_add_u32 v246, v246, 4, v252
	v_lshlrev_b32_e32 v252, 5, v207
	v_sub_u32_e32 v246, v246, v252
	v_lshl_add_u32 v252, v242, 2, s101
	ds_write_b32 v252, v216
	ds_write_b32 v252, v218 offset:256
	ds_write_b32 v252, v220 offset:512
	ds_write_b32 v252, v222 offset:768
	v_and_b32_e32 v206, 3, v242
	v_lshrrev_b32_e32 v204, 2, v242
	v_lshl_add_u32 v205, v206, 4, v204
	v_sub_u32_e32 v204, v204, v211
	v_sub_u32_e32 v206, v206, v207
	v_lshlrev_b32_e32 v204, 11, v204
	v_lshl_add_u32 v204, v206, 4, v204
	v_lshlrev_b32_e32 v206, 2, v205
	v_ashrrev_i32_e32 v205, 31, v204
	v_mov_b32_e32 v106, v211
	v_mov_b32_e32 v250, v207
	s_ashr_i32 s46, s77, 3
	v_lshlrev_b32_e32 v104, 4, v250
	v_add3_u32 v107, s5, v106, v104
	s_lshl_b32 s44, s76, 8
	v_cmp_lt_i32_e32 vcc, 63, v107
	s_mov_b64 s[56:57], 0
	s_and_saveexec_b64 s[54:55], vcc
	s_xor_b64 s[54:55], exec, s[54:55]
	s_movk_i32 s63, 0x5ff
	s_cbranch_execnz .LBB0_261
	s_andn2_saveexec_b64 s[54:55], s[54:55]
	s_cbranch_execnz .LBB0_264

; #define LAS __attribute__((address_space(3)))
; __device__ __forceinline__ unsigned cvt_pk_bf16(float lo, float hi) { const cvt_f32x2_t v = {lo, hi}; const cvt_bf16x2_t b = __builtin_convertvector(v, cvt_bf16x2_t); return __builtin_bit_cast(unsigned, b); }
; __device__ __forceinline__ float sq4(f32x4 v) { return (v[0] * v[0] + v[1] * v[1]) + (v[2] * v[2] + v[3] * v[3]); }
;     __device__ __forceinline__ void operator()(const f32x4 (&acc)[2][2][4][2], const Unit& u, int wr, int wc, int fr, int fq) const {
;     ...
; #pragma unroll
;         for (int ai = 0; ai < 2; ++ai) {
;             f32x4 xr[4][2][2];
; #pragma unroll
;             for (int m = 0; m < 4; ++m) { const size_t off = (size_t)(u.pm * 256 + ai * 128 + wr * 64 + m * 16 + fr) * DM + col0;
; #pragma unroll
;                 for (int bj = 0; bj < 2; ++bj)
; #pragma unroll
;                     for (int n = 0; n < 2; ++n) xr[m][bj][n] = *(const f32x4*)(xin + off + 128 * bj + 4 * n); }
;             asm volatile("" ::: "memory");
; #pragma unroll
;             for (int m = 0; m < 4; ++m) {
;                 const int row = u.pm * 256 + ai * 128 + wr * 64 + m * 16 + fr;
;                 const size_t off = (size_t)row * DM + col0;
;                 float ss = 0.f;
; #pragma unroll
;                 for (int bj = 0; bj < 2; ++bj) {
;                     const f32x4 xo0 = xr[m][bj][0] + *(const LAS f32x4*)(gtp + 128 * bj) * acc[ai][bj][m][0], xo1 = xr[m][bj][1] + *(const LAS f32x4*)(gtp + 128 * bj + 4) * acc[ai][bj][m][1];
;                     *(f32x4*)(xout + off + 128 * bj) = xo0; *(f32x4*)(xout + off + 128 * bj + 4) = xo1;
;                     if (gmn) { ss += sq4(xo0) + sq4(xo1); const f32x4 a = xo0 * *(const LAS f32x4*)(gmp + 128 * bj), c = xo1 * *(const LAS f32x4*)(gmp + 128 * bj + 4);
;                         u32x4 w; w.x = cvt_pk_bf16(a[0], a[1]); w.y = cvt_pk_bf16(a[2], a[3]); w.z = cvt_pk_bf16(c[0], c[1]); w.w = cvt_pk_bf16(c[2], c[3]); *(u32x4*)(AX + off + 128 * bj) = w; }
;                 }
;                 if (gmn) { ss += __shfl_xor(ss, 16); ss += __shfl_xor(ss, 32); if (fq == 0) statx[(size_t)row * 16 + u.pn * 4 + wc] = ss; }
;             }
.LBB0_216:
	s_or_b64 exec, exec, s[46:47]
	s_or_b32 s44, s44, s58
	v_lshl_add_u32 v224, v250, 3, s44
	s_lshl_b32 s44, s77, 8
	s_add_i32 s44, s44, s7
	v_add_u32_e32 v226, s44, v106
	v_readlane_b32 s44, v255, 46
	v_lshlrev_b32_e32 v104, 5, v250
	v_ashrrev_i32_e32 v225, 31, v224
	v_readlane_b32 s45, v255, 47
	v_ashrrev_i32_e32 v227, 31, v226
	v_add_u32_e32 v249, s87, v104
	v_add_u32_e32 v192, s8, v104
	v_lshl_add_u64 v[228:229], v[224:225], 2, s[44:45]
	v_lshlrev_b64 v[104:105], 12, v[226:227]
	v_add_u32_e32 v234, 16, v226
	s_waitcnt vmcnt(0) lgkmcnt(0)
	s_barrier
	v_lshl_add_u64 v[104:105], v[228:229], 0, v[104:105]
	v_ashrrev_i32_e32 v235, 31, v234
	global_load_dwordx4 v[194:197], v[104:105], off offset:16
	global_load_dwordx4 v[198:201], v[104:105], off
	global_load_dwordx4 v[184:187], v[104:105], off offset:528
	global_load_dwordx4 v[188:191], v[104:105], off offset:512
	v_lshlrev_b64 v[104:105], 12, v[234:235]
	v_add_u32_e32 v232, 32, v226
	v_lshl_add_u64 v[104:105], v[228:229], 0, v[104:105]
	v_ashrrev_i32_e32 v233, 31, v232
	global_load_dwordx4 v[176:179], v[104:105], off offset:16
	global_load_dwordx4 v[180:183], v[104:105], off
	global_load_dwordx4 v[168:171], v[104:105], off offset:528
	global_load_dwordx4 v[172:175], v[104:105], off offset:512
	v_lshlrev_b64 v[104:105], 12, v[232:233]
	v_add_u32_e32 v230, 48, v226
	v_lshl_add_u64 v[104:105], v[228:229], 0, v[104:105]
	v_ashrrev_i32_e32 v231, 31, v230
	global_load_dwordx4 v[160:163], v[104:105], off offset:16
	global_load_dwordx4 v[164:167], v[104:105], off
	global_load_dwordx4 v[152:155], v[104:105], off offset:528
	global_load_dwordx4 v[156:159], v[104:105], off offset:512
	v_lshlrev_b64 v[104:105], 12, v[230:231]
	v_lshl_add_u64 v[112:113], v[228:229], 0, v[104:105]
	global_load_dwordx4 v[136:139], v[112:113], off offset:16
	global_load_dwordx4 v[144:147], v[112:113], off
	global_load_dwordx4 v[104:107], v[112:113], off offset:528
	s_nop 0
	global_load_dwordx4 v[112:115], v[112:113], off offset:512
	v_lshlrev_b64 v[140:141], 10, v[226:227]
	v_lshl_add_u64 v[202:203], v[140:141], 0, v[224:225]
	ds_read_b128 v[148:151], v249
	ds_read_b128 v[140:143], v249 offset:16
	v_lshl_add_u64 v[236:237], v[202:203], 2, s[20:21]
	v_lshl_add_u32 v236, v202, 2, v246
	v_mov_b32_e32 v251, 0
	s_andn2_b64 vcc, exec, s[40:41]
	v_lshl_add_u64 v[238:239], v[202:203], 1, s[16:17]
	v_lshl_add_u64 v[238:239], v[204:205], 0, v[238:239]
	s_waitcnt vmcnt(0) lgkmcnt(0)
	v_pk_fma_f32 v[128:129], v[128:129], v[140:141], v[194:195]
	v_cndmask_b32_e64 v194, 0, 1, s[40:41]
	v_pk_fma_f32 v[134:135], v[134:135], v[150:151], v[200:201]
	v_pk_fma_f32 v[132:133], v[132:133], v[148:149], v[198:199]
	v_pk_fma_f32 v[130:131], v[130:131], v[142:143], v[196:197]
	v_cmp_ne_u32_e64 s[46:47], 1, v194
	ds_write_b128 v208, v[132:135]
	ds_write_b128 v208, v[128:131] offset:16
	ds_read_b128 v[216:219], v210
	ds_read_b128 v[220:223], v210 offset:64
	s_waitcnt lgkmcnt(0)
	global_store_dwordx4 v236, v[216:219], s[20:21]
	global_store_dwordx4 v236, v[220:223], s[20:21] offset:64
	s_cbranch_vccnz .LBB0_218
	v_mov_b32_e32 v196, v133
	v_mov_b32_e32 v197, v129
	v_mov_b32_e32 v194, v132
	v_mov_b32_e32 v195, v128
	v_pk_mul_f32 v[196:197], v[196:197], v[196:197]
	v_mov_b32_e32 v198, v135
	v_mov_b32_e32 v199, v131
	v_pk_fma_f32 v[194:195], v[194:195], v[194:195], v[196:197]
	v_mov_b32_e32 v196, v134
	v_mov_b32_e32 v197, v130
	v_pk_mul_f32 v[198:199], v[198:199], v[198:199]
	s_nop 0
	v_pk_fma_f32 v[196:197], v[196:197], v[196:197], v[198:199]
	s_nop 0
	v_pk_add_f32 v[194:195], v[194:195], v[196:197]
	s_nop 0
	v_add_f32_e32 v251, v194, v195
	ds_read_b128 v[194:197], v192
	ds_read_b128 v[198:201], v192 offset:16
	s_waitcnt lgkmcnt(1)
	v_pk_mul_f32 v[134:135], v[134:135], v[196:197]
	v_pk_mul_f32 v[132:133], v[132:133], v[194:195]
	s_waitcnt lgkmcnt(0)
	v_pk_mul_f32 v[194:195], v[130:131], v[200:201]
	v_pk_mul_f32 v[130:131], v[128:129], v[198:199]
	v_cvt_pk_bf16_f32 v128, v132, v133
	v_cvt_pk_bf16_f32 v129, v134, v135
	v_cvt_pk_bf16_f32 v130, v130, v131
	v_cvt_pk_bf16_f32 v131, v194, v195
	ds_bpermute_b32 v128, v206, v128
	ds_bpermute_b32 v129, v206, v129
	ds_bpermute_b32 v130, v206, v130
	ds_bpermute_b32 v131, v206, v131
	s_waitcnt lgkmcnt(0)
	global_store_dwordx4 v[238:239], v[128:131], off
.LBB0_218:
	ds_read_b128 v[132:135], v249 offset:512
	ds_read_b128 v[128:131], v249 offset:528
	s_lshl_b32 s76, s76, 2
	v_cmp_eq_u32_e64 s[44:45], 0, v250
	s_ashr_i32 s77, s76, 31
	s_waitcnt lgkmcnt(1)
	v_pk_fma_f32 v[126:127], v[126:127], v[134:135], v[190:191]
	v_pk_fma_f32 v[124:125], v[124:125], v[132:133], v[188:189]
	s_waitcnt lgkmcnt(0)
	v_pk_fma_f32 v[122:123], v[122:123], v[130:131], v[186:187]
	v_pk_fma_f32 v[120:121], v[120:121], v[128:129], v[184:185]
	s_and_b64 vcc, exec, s[46:47]
	ds_write_b128 v208, v[124:127]
	ds_write_b128 v208, v[120:123] offset:16
	ds_read_b128 v[216:219], v210
	ds_read_b128 v[220:223], v210 offset:64
	s_waitcnt lgkmcnt(0)
	global_store_dwordx4 v236, v[216:219], s[20:21] offset:512
	global_store_dwordx4 v236, v[220:223], s[20:21] offset:576
	s_cbranch_vccnz .LBB0_222
	ds_read_b128 v[184:187], v192 offset:512
	ds_read_b128 v[188:191], v192 offset:528
	s_waitcnt lgkmcnt(1)
	v_pk_mul_f32 v[184:185], v[124:125], v[184:185]
	s_waitcnt lgkmcnt(0)
	v_pk_mul_f32 v[188:189], v[120:121], v[188:189]
	v_mul_f32_e32 v121, v121, v121
	v_mul_f32_e32 v125, v125, v125
	v_fmac_f32_e32 v121, v120, v120
	v_mul_f32_e32 v120, v123, v123
	v_pk_mul_f32 v[190:191], v[122:123], v[190:191]
	v_fmac_f32_e32 v125, v124, v124
	v_mul_f32_e32 v124, v127, v127
	v_fmac_f32_e32 v120, v122, v122
	v_and_b32_e32 v122, 64, v242
	v_fmac_f32_e32 v124, v126, v126
	v_add_f32_e32 v120, v121, v120
	v_xor_b32_e32 v121, 16, v242
	v_add_u32_e32 v122, 64, v122
	v_add_f32_e32 v124, v125, v124
	v_cmp_lt_i32_e32 vcc, v121, v122
	v_add_f32_e32 v120, v124, v120
	v_add_f32_e32 v120, v251, v120
	v_cndmask_b32_e32 v121, v242, v121, vcc
	v_lshlrev_b32_e32 v121, 2, v121
	ds_bpermute_b32 v121, v121, v120
	v_pk_mul_f32 v[186:187], v[126:127], v[186:187]
	v_cvt_pk_bf16_f32 v184, v184, v185
	v_cvt_pk_bf16_f32 v185, v186, v187
	v_cvt_pk_bf16_f32 v186, v188, v189
	s_waitcnt lgkmcnt(0)
	v_add_f32_e32 v120, v120, v121
	v_xor_b32_e32 v121, 32, v242
	v_cmp_lt_i32_e32 vcc, v121, v122
	v_cvt_pk_bf16_f32 v187, v190, v191
	ds_bpermute_b32 v184, v206, v184
	ds_bpermute_b32 v185, v206, v185
	ds_bpermute_b32 v186, v206, v186
	ds_bpermute_b32 v187, v206, v187
	s_waitcnt lgkmcnt(0)
	global_store_dwordx4 v[238:239], v[184:187], off offset:256
	v_cndmask_b32_e32 v121, v242, v121, vcc
	v_lshlrev_b32_e32 v121, 2, v121
	ds_bpermute_b32 v121, v121, v120
	s_and_saveexec_b64 s[54:55], s[44:45]
	s_cbranch_execz .LBB0_221
	v_lshlrev_b64 v[122:123], 6, v[226:227]
	v_lshl_add_u64 v[122:123], s[22:23], 0, v[122:123]
	v_lshl_add_u64 v[122:123], s[76:77], 2, v[122:123]
	s_lshl_b32 s92, s6, 2
	v_lshl_add_u64 v[122:123], v[122:123], 0, s[92:93]
	s_waitcnt lgkmcnt(0)
	v_add_f32_e32 v120, v120, v121
	global_store_dword v[122:123], v120, off

; #define LAS __attribute__((address_space(3)))
; __device__ __forceinline__ unsigned cvt_pk_bf16(float lo, float hi) { const cvt_f32x2_t v = {lo, hi}; const cvt_bf16x2_t b = __builtin_convertvector(v, cvt_bf16x2_t); return __builtin_bit_cast(unsigned, b); }
; __device__ __forceinline__ float sq4(f32x4 v) { return (v[0] * v[0] + v[1] * v[1]) + (v[2] * v[2] + v[3] * v[3]); }
;     __device__ __forceinline__ void operator()(const f32x4 (&acc)[2][2][4][2], const Unit& u, int wr, int wc, int fr, int fq) const {
;     ...
; #pragma unroll
;         for (int ai = 0; ai < 2; ++ai) {
;             f32x4 xr[4][2][2];
; #pragma unroll
;             for (int m = 0; m < 4; ++m) { const size_t off = (size_t)(u.pm * 256 + ai * 128 + wr * 64 + m * 16 + fr) * DM + col0;
; #pragma unroll
;                 for (int bj = 0; bj < 2; ++bj)
; #pragma unroll
;                     for (int n = 0; n < 2; ++n) xr[m][bj][n] = *(const f32x4*)(xin + off + 128 * bj + 4 * n); }
;             asm volatile("" ::: "memory");
; #pragma unroll
;             for (int m = 0; m < 4; ++m) {
;                 const int row = u.pm * 256 + ai * 128 + wr * 64 + m * 16 + fr;
;                 const size_t off = (size_t)row * DM + col0;
;                 float ss = 0.f;
; #pragma unroll
;                 for (int bj = 0; bj < 2; ++bj) {
;                     const f32x4 xo0 = xr[m][bj][0] + *(const LAS f32x4*)(gtp + 128 * bj) * acc[ai][bj][m][0], xo1 = xr[m][bj][1] + *(const LAS f32x4*)(gtp + 128 * bj + 4) * acc[ai][bj][m][1];
;                     *(f32x4*)(xout + off + 128 * bj) = xo0; *(f32x4*)(xout + off + 128 * bj + 4) = xo1;
;                     if (gmn) { ss += sq4(xo0) + sq4(xo1); const f32x4 a = xo0 * *(const LAS f32x4*)(gmp + 128 * bj), c = xo1 * *(const LAS f32x4*)(gmp + 128 * bj + 4);
;                         u32x4 w; w.x = cvt_pk_bf16(a[0], a[1]); w.y = cvt_pk_bf16(a[2], a[3]); w.z = cvt_pk_bf16(c[0], c[1]); w.w = cvt_pk_bf16(c[2], c[3]); *(u32x4*)(AX + off + 128 * bj) = w; }
;                 }
;                 if (gmn) { ss += __shfl_xor(ss, 16); ss += __shfl_xor(ss, 32); if (fq == 0) statx[(size_t)row * 16 + u.pn * 4 + wc] = ss; }
;             }
.LBB0_222:
	s_waitcnt lgkmcnt(0)
	v_lshlrev_b64 v[120:121], 10, v[234:235]
	v_lshl_add_u64 v[184:185], v[120:121], 0, v[224:225]
	v_pk_fma_f32 v[120:121], v[118:119], v[150:151], v[182:183]
	v_pk_fma_f32 v[118:119], v[116:117], v[148:149], v[180:181]
	v_pk_fma_f32 v[124:125], v[110:111], v[142:143], v[178:179]
	v_pk_fma_f32 v[122:123], v[108:109], v[140:141], v[176:177]
	v_lshl_add_u64 v[126:127], v[184:185], 2, s[20:21]
	v_lshl_add_u32 v126, v184, 2, v246
	s_mov_b64 s[54:55], -1
	s_and_b64 vcc, exec, s[46:47]
	v_pk_fma_f32 v[116:117], v[100:101], v[132:133], v[172:173]
	v_pk_fma_f32 v[108:109], v[92:93], v[128:129], v[168:169]
	ds_write_b128 v208, v[118:121]
	ds_write_b128 v208, v[122:125] offset:16
	ds_read_b128 v[216:219], v210
	ds_read_b128 v[220:223], v210 offset:64
	s_waitcnt lgkmcnt(0)
	global_store_dwordx4 v126, v[216:219], s[20:21]
	global_store_dwordx4 v126, v[220:223], s[20:21] offset:64
	s_cbranch_vccnz .LBB0_226
	v_mul_f32_e32 v92, v119, v119
	v_mul_f32_e32 v93, v121, v121
	ds_read_b128 v[176:179], v192
	ds_read_b128 v[180:183], v192 offset:16
	v_fmac_f32_e32 v92, v118, v118
	v_fmac_f32_e32 v93, v120, v120
	v_add_f32_e32 v92, v92, v93
	v_mul_f32_e32 v93, v123, v123
	v_mul_f32_e32 v100, v125, v125
	v_fmac_f32_e32 v93, v122, v122
	v_fmac_f32_e32 v100, v124, v124
	v_add_f32_e32 v93, v93, v100
	v_add_f32_e32 v172, v92, v93
	s_waitcnt lgkmcnt(1)
	v_pk_mul_f32 v[92:93], v[120:121], v[178:179]
	v_pk_mul_f32 v[100:101], v[118:119], v[176:177]
	s_waitcnt lgkmcnt(0)
	v_pk_mul_f32 v[110:111], v[124:125], v[182:183]
	v_pk_mul_f32 v[120:121], v[122:123], v[180:181]
	v_cvt_pk_bf16_f32 v118, v100, v101
	v_cvt_pk_bf16_f32 v119, v92, v93
	v_cvt_pk_bf16_f32 v120, v120, v121
	v_cvt_pk_bf16_f32 v121, v110, v111
	v_lshl_add_u64 v[92:93], v[184:185], 1, s[16:17]
	ds_bpermute_b32 v118, v206, v118
	ds_bpermute_b32 v119, v206, v119
	ds_bpermute_b32 v120, v206, v120
	ds_bpermute_b32 v121, v206, v121
	s_waitcnt lgkmcnt(0)
	v_lshl_add_u64 v[92:93], v[204:205], 0, v[92:93]
	global_store_dwordx4 v[92:93], v[118:121], off
	v_pk_fma_f32 v[110:111], v[94:95], v[130:131], v[170:171]
	s_nop 0
	v_pk_fma_f32 v[118:119], v[102:103], v[134:135], v[174:175]
	ds_write_b128 v208, v[116:119]
	ds_write_b128 v208, v[108:111] offset:16
	ds_read_b128 v[216:219], v210
	ds_read_b128 v[220:223], v210 offset:64
	s_waitcnt lgkmcnt(0)
	global_store_dwordx4 v126, v[216:219], s[20:21] offset:512
	global_store_dwordx4 v126, v[220:223], s[20:21] offset:576
	ds_read_b128 v[120:123], v192 offset:512
	s_waitcnt lgkmcnt(0)
	v_pk_mul_f32 v[100:101], v[118:119], v[122:123]
	v_pk_mul_f32 v[124:125], v[116:117], v[120:121]
	ds_read_b128 v[120:123], v192 offset:528
	s_waitcnt lgkmcnt(0)
	v_pk_mul_f32 v[168:169], v[110:111], v[122:123]
	v_pk_mul_f32 v[122:123], v[108:109], v[120:121]
	v_cvt_pk_bf16_f32 v120, v124, v125
	v_cvt_pk_bf16_f32 v121, v100, v101
	v_cvt_pk_bf16_f32 v122, v122, v123
	v_cvt_pk_bf16_f32 v123, v168, v169
	ds_bpermute_b32 v120, v206, v120
	ds_bpermute_b32 v121, v206, v121
	ds_bpermute_b32 v122, v206, v122
	ds_bpermute_b32 v123, v206, v123
	s_waitcnt lgkmcnt(0)
	global_store_dwordx4 v[92:93], v[120:123], off offset:256
	v_mul_f32_e32 v92, v117, v117
	v_mul_f32_e32 v93, v119, v119
	v_fmac_f32_e32 v92, v116, v116
	v_fmac_f32_e32 v93, v118, v118
	v_add_f32_e32 v92, v92, v93
	v_mul_f32_e32 v93, v109, v109
	v_mul_f32_e32 v100, v111, v111
	v_fmac_f32_e32 v93, v108, v108
	v_fmac_f32_e32 v100, v110, v110
	v_add_f32_e32 v93, v93, v100
	v_and_b32_e32 v100, 64, v242
	v_add_f32_e32 v92, v92, v93
	v_xor_b32_e32 v93, 16, v242
	v_add_u32_e32 v100, 64, v100
	v_cmp_lt_i32_e32 vcc, v93, v100
	v_add_f32_e32 v92, v172, v92
	s_nop 0
	v_cndmask_b32_e32 v93, v242, v93, vcc
	v_lshlrev_b32_e32 v93, 2, v93
	ds_bpermute_b32 v93, v93, v92
	s_waitcnt lgkmcnt(0)
	v_add_f32_e32 v92, v92, v93
	v_xor_b32_e32 v93, 32, v242
	v_cmp_lt_i32_e32 vcc, v93, v100
	s_nop 1
	v_cndmask_b32_e32 v93, v242, v93, vcc
	v_lshlrev_b32_e32 v93, 2, v93
	ds_bpermute_b32 v93, v93, v92
	s_and_saveexec_b64 s[54:55], s[44:45]
	s_cbranch_execz .LBB0_225
	v_lshlrev_b64 v[100:101], 6, v[234:235]
	v_lshl_add_u64 v[100:101], s[22:23], 0, v[100:101]
	v_lshl_add_u64 v[100:101], s[76:77], 2, v[100:101]
	s_lshl_b32 s92, s6, 2
	v_lshl_add_u64 v[100:101], v[100:101], 0, s[92:93]
	s_waitcnt lgkmcnt(0)
	v_add_f32_e32 v92, v92, v93
	global_store_dword v[100:101], v92, off

; #define LAS __attribute__((address_space(3)))
; __device__ __forceinline__ unsigned cvt_pk_bf16(float lo, float hi) { const cvt_f32x2_t v = {lo, hi}; const cvt_bf16x2_t b = __builtin_convertvector(v, cvt_bf16x2_t); return __builtin_bit_cast(unsigned, b); }
; __device__ __forceinline__ float sq4(f32x4 v) { return (v[0] * v[0] + v[1] * v[1]) + (v[2] * v[2] + v[3] * v[3]); }
;     __device__ __forceinline__ void operator()(const f32x4 (&acc)[2][2][4][2], const Unit& u, int wr, int wc, int fr, int fq) const {
;     ...
; #pragma unroll
;         for (int ai = 0; ai < 2; ++ai) {
;             f32x4 xr[4][2][2];
; #pragma unroll
;             for (int m = 0; m < 4; ++m) { const size_t off = (size_t)(u.pm * 256 + ai * 128 + wr * 64 + m * 16 + fr) * DM + col0;
; #pragma unroll
;                 for (int bj = 0; bj < 2; ++bj)
; #pragma unroll
;                     for (int n = 0; n < 2; ++n) xr[m][bj][n] = *(const f32x4*)(xin + off + 128 * bj + 4 * n); }
;             asm volatile("" ::: "memory");
; #pragma unroll
;             for (int m = 0; m < 4; ++m) {
;                 const int row = u.pm * 256 + ai * 128 + wr * 64 + m * 16 + fr;
;                 const size_t off = (size_t)row * DM + col0;
;                 float ss = 0.f;
; #pragma unroll
;                 for (int bj = 0; bj < 2; ++bj) {
;                     const f32x4 xo0 = xr[m][bj][0] + *(const LAS f32x4*)(gtp + 128 * bj) * acc[ai][bj][m][0], xo1 = xr[m][bj][1] + *(const LAS f32x4*)(gtp + 128 * bj + 4) * acc[ai][bj][m][1];
;                     *(f32x4*)(xout + off + 128 * bj) = xo0; *(f32x4*)(xout + off + 128 * bj + 4) = xo1;
;                     if (gmn) { ss += sq4(xo0) + sq4(xo1); const f32x4 a = xo0 * *(const LAS f32x4*)(gmp + 128 * bj), c = xo1 * *(const LAS f32x4*)(gmp + 128 * bj + 4);
;                         u32x4 w; w.x = cvt_pk_bf16(a[0], a[1]); w.y = cvt_pk_bf16(a[2], a[3]); w.z = cvt_pk_bf16(c[0], c[1]); w.w = cvt_pk_bf16(c[2], c[3]); *(u32x4*)(AX + off + 128 * bj) = w; }
;                 }
;                 if (gmn) { ss += __shfl_xor(ss, 16); ss += __shfl_xor(ss, 32); if (fq == 0) statx[(size_t)row * 16 + u.pn * 4 + wc] = ss; }
;             }
.LBB0_226:
	s_andn2_b64 vcc, exec, s[54:55]
	s_cbranch_vccnz .LBB0_228
	v_pk_fma_f32 v[118:119], v[102:103], v[134:135], v[174:175]
	v_pk_fma_f32 v[110:111], v[94:95], v[130:131], v[170:171]
	ds_write_b128 v208, v[116:119]
	ds_write_b128 v208, v[108:111] offset:16
	ds_read_b128 v[216:219], v210
	ds_read_b128 v[220:223], v210 offset:64
	s_waitcnt lgkmcnt(0)
	global_store_dwordx4 v126, v[216:219], s[20:21] offset:512
	global_store_dwordx4 v126, v[220:223], s[20:21] offset:576
.LBB0_228:
	s_waitcnt lgkmcnt(0)
	v_lshlrev_b64 v[92:93], 10, v[232:233]
	v_lshl_add_u64 v[94:95], v[92:93], 0, v[224:225]
	v_pk_fma_f32 v[98:99], v[98:99], v[150:151], v[166:167]
	v_pk_fma_f32 v[96:97], v[96:97], v[148:149], v[164:165]
	v_pk_fma_f32 v[102:103], v[90:91], v[142:143], v[162:163]
	v_pk_fma_f32 v[100:101], v[88:89], v[140:141], v[160:161]
	v_lshl_add_u64 v[108:109], v[94:95], 2, s[20:21]
	v_lshl_add_u32 v108, v94, 2, v246
	s_mov_b64 s[54:55], -1
	s_and_b64 vcc, exec, s[46:47]
	v_pk_fma_f32 v[92:93], v[84:85], v[132:133], v[156:157]
	v_pk_fma_f32 v[88:89], v[76:77], v[128:129], v[152:153]
	ds_write_b128 v208, v[96:99]
	ds_write_b128 v208, v[100:103] offset:16
	ds_read_b128 v[216:219], v210
	ds_read_b128 v[220:223], v210 offset:64
	s_waitcnt lgkmcnt(0)
	global_store_dwordx4 v108, v[216:219], s[20:21]
	global_store_dwordx4 v108, v[220:223], s[20:21] offset:64
	s_cbranch_vccnz .LBB0_232
	v_mul_f32_e32 v76, v97, v97
	v_mul_f32_e32 v77, v99, v99
	ds_read_b128 v[116:119], v192
	ds_read_b128 v[120:123], v192 offset:16
	v_fmac_f32_e32 v76, v96, v96
	v_fmac_f32_e32 v77, v98, v98
	v_add_f32_e32 v76, v76, v77
	v_mul_f32_e32 v77, v101, v101
	v_mul_f32_e32 v84, v103, v103
	v_fmac_f32_e32 v77, v100, v100
	v_fmac_f32_e32 v84, v102, v102
	v_add_f32_e32 v77, v77, v84
	v_add_f32_e32 v110, v76, v77
	s_waitcnt lgkmcnt(1)
	v_pk_mul_f32 v[76:77], v[98:99], v[118:119]
	v_pk_mul_f32 v[84:85], v[96:97], v[116:117]
	s_waitcnt lgkmcnt(0)
	v_pk_mul_f32 v[90:91], v[102:103], v[122:123]
	v_pk_mul_f32 v[98:99], v[100:101], v[120:121]
	v_cvt_pk_bf16_f32 v96, v84, v85
	v_cvt_pk_bf16_f32 v97, v76, v77
	v_cvt_pk_bf16_f32 v98, v98, v99
	v_cvt_pk_bf16_f32 v99, v90, v91
	v_lshl_add_u64 v[76:77], v[94:95], 1, s[16:17]
	v_lshl_add_u64 v[76:77], v[204:205], 0, v[76:77]
	v_pk_fma_f32 v[94:95], v[86:87], v[134:135], v[158:159]
	ds_bpermute_b32 v96, v206, v96
	ds_bpermute_b32 v97, v206, v97
	ds_bpermute_b32 v98, v206, v98
	ds_bpermute_b32 v99, v206, v99
	s_waitcnt lgkmcnt(0)
	global_store_dwordx4 v[76:77], v[96:99], off
	v_pk_fma_f32 v[90:91], v[78:79], v[130:131], v[154:155]
	ds_write_b128 v208, v[92:95]
	ds_write_b128 v208, v[88:91] offset:16
	ds_read_b128 v[216:219], v210
	ds_read_b128 v[220:223], v210 offset:64
	s_waitcnt lgkmcnt(0)
	global_store_dwordx4 v108, v[216:219], s[20:21] offset:512
	global_store_dwordx4 v108, v[220:223], s[20:21] offset:576
	ds_read_b128 v[96:99], v192 offset:512
	s_waitcnt lgkmcnt(0)
	v_pk_mul_f32 v[84:85], v[94:95], v[98:99]
	v_pk_mul_f32 v[100:101], v[92:93], v[96:97]
	ds_read_b128 v[96:99], v192 offset:528
	s_waitcnt lgkmcnt(0)
	v_pk_mul_f32 v[102:103], v[90:91], v[98:99]
	v_pk_mul_f32 v[98:99], v[88:89], v[96:97]
	v_cvt_pk_bf16_f32 v96, v100, v101
	v_cvt_pk_bf16_f32 v97, v84, v85
	v_cvt_pk_bf16_f32 v98, v98, v99
	v_cvt_pk_bf16_f32 v99, v102, v103
	ds_bpermute_b32 v96, v206, v96
	ds_bpermute_b32 v97, v206, v97
	ds_bpermute_b32 v98, v206, v98
	ds_bpermute_b32 v99, v206, v99
	s_waitcnt lgkmcnt(0)
	global_store_dwordx4 v[76:77], v[96:99], off offset:256
	v_mul_f32_e32 v76, v93, v93
	v_mul_f32_e32 v77, v95, v95
	v_fmac_f32_e32 v76, v92, v92
	v_fmac_f32_e32 v77, v94, v94
	v_add_f32_e32 v76, v76, v77
	v_mul_f32_e32 v77, v89, v89
	v_mul_f32_e32 v84, v91, v91
	v_fmac_f32_e32 v77, v88, v88
	v_fmac_f32_e32 v84, v90, v90
	v_add_f32_e32 v77, v77, v84
	v_and_b32_e32 v84, 64, v242
	v_add_f32_e32 v76, v76, v77
	v_xor_b32_e32 v77, 16, v242
	v_add_u32_e32 v84, 64, v84
	v_cmp_lt_i32_e32 vcc, v77, v84
	v_add_f32_e32 v76, v110, v76
	s_nop 0
	v_cndmask_b32_e32 v77, v242, v77, vcc
	v_lshlrev_b32_e32 v77, 2, v77
	ds_bpermute_b32 v77, v77, v76
	s_waitcnt lgkmcnt(0)
	v_add_f32_e32 v76, v76, v77
	v_xor_b32_e32 v77, 32, v242
	v_cmp_lt_i32_e32 vcc, v77, v84
	s_nop 1
	v_cndmask_b32_e32 v77, v242, v77, vcc
	v_lshlrev_b32_e32 v77, 2, v77
	ds_bpermute_b32 v77, v77, v76
	s_and_saveexec_b64 s[54:55], s[44:45]
	s_cbranch_execz .LBB0_231
	v_lshlrev_b64 v[84:85], 6, v[232:233]
	v_lshl_add_u64 v[84:85], s[22:23], 0, v[84:85]
	v_lshl_add_u64 v[84:85], s[76:77], 2, v[84:85]
	s_lshl_b32 s92, s6, 2
	v_lshl_add_u64 v[84:85], v[84:85], 0, s[92:93]
	s_waitcnt lgkmcnt(0)
	v_add_f32_e32 v76, v76, v77
	global_store_dword v[84:85], v76, off

; #define LAS __attribute__((address_space(3)))
; __device__ __forceinline__ unsigned cvt_pk_bf16(float lo, float hi) { const cvt_f32x2_t v = {lo, hi}; const cvt_bf16x2_t b = __builtin_convertvector(v, cvt_bf16x2_t); return __builtin_bit_cast(unsigned, b); }
; __device__ __forceinline__ float sq4(f32x4 v) { return (v[0] * v[0] + v[1] * v[1]) + (v[2] * v[2] + v[3] * v[3]); }
;     __device__ __forceinline__ void operator()(const f32x4 (&acc)[2][2][4][2], const Unit& u, int wr, int wc, int fr, int fq) const {
;     ...
; #pragma unroll
;         for (int ai = 0; ai < 2; ++ai) {
;             f32x4 xr[4][2][2];
; #pragma unroll
;             for (int m = 0; m < 4; ++m) { const size_t off = (size_t)(u.pm * 256 + ai * 128 + wr * 64 + m * 16 + fr) * DM + col0;
; #pragma unroll
;                 for (int bj = 0; bj < 2; ++bj)
; #pragma unroll
;                     for (int n = 0; n < 2; ++n) xr[m][bj][n] = *(const f32x4*)(xin + off + 128 * bj + 4 * n); }
;             asm volatile("" ::: "memory");
; #pragma unroll
;             for (int m = 0; m < 4; ++m) {
;                 const int row = u.pm * 256 + ai * 128 + wr * 64 + m * 16 + fr;
;                 const size_t off = (size_t)row * DM + col0;
;                 float ss = 0.f;
; #pragma unroll
;                 for (int bj = 0; bj < 2; ++bj) {
;                     const f32x4 xo0 = xr[m][bj][0] + *(const LAS f32x4*)(gtp + 128 * bj) * acc[ai][bj][m][0], xo1 = xr[m][bj][1] + *(const LAS f32x4*)(gtp + 128 * bj + 4) * acc[ai][bj][m][1];
;                     *(f32x4*)(xout + off + 128 * bj) = xo0; *(f32x4*)(xout + off + 128 * bj + 4) = xo1;
;                     if (gmn) { ss += sq4(xo0) + sq4(xo1); const f32x4 a = xo0 * *(const LAS f32x4*)(gmp + 128 * bj), c = xo1 * *(const LAS f32x4*)(gmp + 128 * bj + 4);
;                         u32x4 w; w.x = cvt_pk_bf16(a[0], a[1]); w.y = cvt_pk_bf16(a[2], a[3]); w.z = cvt_pk_bf16(c[0], c[1]); w.w = cvt_pk_bf16(c[2], c[3]); *(u32x4*)(AX + off + 128 * bj) = w; }
;                 }
;                 if (gmn) { ss += __shfl_xor(ss, 16); ss += __shfl_xor(ss, 32); if (fq == 0) statx[(size_t)row * 16 + u.pn * 4 + wc] = ss; }
;             }
.LBB0_232:
	s_andn2_b64 vcc, exec, s[54:55]
	s_cbranch_vccnz .LBB0_234
	v_pk_fma_f32 v[94:95], v[86:87], v[134:135], v[158:159]
	v_pk_fma_f32 v[90:91], v[78:79], v[130:131], v[154:155]
	ds_write_b128 v208, v[92:95]
	ds_write_b128 v208, v[88:91] offset:16
	ds_read_b128 v[216:219], v210
	ds_read_b128 v[220:223], v210 offset:64
	s_waitcnt lgkmcnt(0)
	global_store_dwordx4 v108, v[216:219], s[20:21] offset:512
	global_store_dwordx4 v108, v[220:223], s[20:21] offset:576
.LBB0_234:
	s_waitcnt lgkmcnt(0)
	v_lshlrev_b64 v[76:77], 10, v[230:231]
	v_lshl_add_u64 v[78:79], v[76:77], 0, v[224:225]
	v_pk_fma_f32 v[82:83], v[82:83], v[150:151], v[146:147]
	v_pk_fma_f32 v[80:81], v[80:81], v[148:149], v[144:145]
	v_pk_fma_f32 v[86:87], v[74:75], v[142:143], v[138:139]
	v_pk_fma_f32 v[84:85], v[72:73], v[140:141], v[136:137]
	v_lshl_add_u64 v[88:89], v[78:79], 2, s[20:21]
	v_lshl_add_u32 v88, v78, 2, v246
	s_mov_b64 s[54:55], -1
	s_and_b64 vcc, exec, s[46:47]
	v_pk_fma_f32 v[76:77], v[68:69], v[132:133], v[112:113]
	v_pk_fma_f32 v[72:73], v[64:65], v[128:129], v[104:105]
	ds_write_b128 v208, v[80:83]
	ds_write_b128 v208, v[84:87] offset:16
	ds_read_b128 v[216:219], v210
	ds_read_b128 v[220:223], v210 offset:64
	s_waitcnt lgkmcnt(0)
	global_store_dwordx4 v88, v[216:219], s[20:21]
	global_store_dwordx4 v88, v[220:223], s[20:21] offset:64
	s_cbranch_vccnz .LBB0_238
	v_mul_f32_e32 v64, v81, v81
	v_mul_f32_e32 v65, v83, v83
	ds_read_b128 v[90:93], v192
	ds_read_b128 v[94:97], v192 offset:16
	v_fmac_f32_e32 v64, v80, v80
	v_fmac_f32_e32 v65, v82, v82
	v_add_f32_e32 v64, v64, v65
	v_mul_f32_e32 v65, v85, v85
	v_mul_f32_e32 v68, v87, v87
	v_fmac_f32_e32 v65, v84, v84
	v_fmac_f32_e32 v68, v86, v86
	v_add_f32_e32 v65, v65, v68
	v_add_f32_e32 v98, v64, v65
	s_waitcnt lgkmcnt(1)
	v_pk_mul_f32 v[64:65], v[82:83], v[92:93]
	v_pk_mul_f32 v[68:69], v[80:81], v[90:91]
	s_waitcnt lgkmcnt(0)
	v_pk_mul_f32 v[74:75], v[86:87], v[96:97]
	v_pk_mul_f32 v[82:83], v[84:85], v[94:95]
	v_cvt_pk_bf16_f32 v80, v68, v69
	v_cvt_pk_bf16_f32 v81, v64, v65
	v_cvt_pk_bf16_f32 v82, v82, v83
	v_cvt_pk_bf16_f32 v83, v74, v75
	v_lshl_add_u64 v[64:65], v[78:79], 1, s[16:17]
	v_lshl_add_u64 v[64:65], v[204:205], 0, v[64:65]
	v_pk_fma_f32 v[78:79], v[70:71], v[134:135], v[114:115]
	ds_bpermute_b32 v80, v206, v80
	ds_bpermute_b32 v81, v206, v81
	ds_bpermute_b32 v82, v206, v82
	ds_bpermute_b32 v83, v206, v83
	s_waitcnt lgkmcnt(0)
	global_store_dwordx4 v[64:65], v[80:83], off
	v_pk_fma_f32 v[74:75], v[66:67], v[130:131], v[106:107]
	ds_write_b128 v208, v[76:79]
	ds_write_b128 v208, v[72:75] offset:16
	ds_read_b128 v[216:219], v210
	ds_read_b128 v[220:223], v210 offset:64
	s_waitcnt lgkmcnt(0)
	global_store_dwordx4 v88, v[216:219], s[20:21] offset:512
	global_store_dwordx4 v88, v[220:223], s[20:21] offset:576
	ds_read_b128 v[80:83], v192 offset:512
	s_waitcnt lgkmcnt(0)
	v_pk_mul_f32 v[68:69], v[78:79], v[82:83]
	v_pk_mul_f32 v[84:85], v[76:77], v[80:81]
	ds_read_b128 v[80:83], v192 offset:528
	s_waitcnt lgkmcnt(0)
	v_pk_mul_f32 v[86:87], v[74:75], v[82:83]
	v_pk_mul_f32 v[82:83], v[72:73], v[80:81]
	v_cvt_pk_bf16_f32 v80, v84, v85
	v_cvt_pk_bf16_f32 v81, v68, v69
	v_cvt_pk_bf16_f32 v82, v82, v83
	v_cvt_pk_bf16_f32 v83, v86, v87
	ds_bpermute_b32 v80, v206, v80
	ds_bpermute_b32 v81, v206, v81
	ds_bpermute_b32 v82, v206, v82
	ds_bpermute_b32 v83, v206, v83
	s_waitcnt lgkmcnt(0)
	global_store_dwordx4 v[64:65], v[80:83], off offset:256
	v_mul_f32_e32 v64, v77, v77
	v_mul_f32_e32 v65, v79, v79
	v_fmac_f32_e32 v64, v76, v76
	v_fmac_f32_e32 v65, v78, v78
	v_add_f32_e32 v64, v64, v65
	v_mul_f32_e32 v65, v73, v73
	v_mul_f32_e32 v68, v75, v75
	v_fmac_f32_e32 v65, v72, v72
	v_fmac_f32_e32 v68, v74, v74
	v_add_f32_e32 v65, v65, v68
	v_and_b32_e32 v68, 64, v242
	v_add_f32_e32 v64, v64, v65
	v_xor_b32_e32 v65, 16, v242
	v_add_u32_e32 v68, 64, v68
	v_cmp_lt_i32_e32 vcc, v65, v68
	v_add_f32_e32 v64, v98, v64
	s_nop 0
	v_cndmask_b32_e32 v65, v242, v65, vcc
	v_lshlrev_b32_e32 v65, 2, v65
	ds_bpermute_b32 v65, v65, v64
	s_waitcnt lgkmcnt(0)
	v_add_f32_e32 v64, v64, v65
	v_xor_b32_e32 v65, 32, v242
	v_cmp_lt_i32_e32 vcc, v65, v68
	s_nop 1
	v_cndmask_b32_e32 v65, v242, v65, vcc
	v_lshlrev_b32_e32 v65, 2, v65
	ds_bpermute_b32 v65, v65, v64
	s_and_saveexec_b64 s[54:55], s[44:45]
	s_cbranch_execz .LBB0_237
	v_lshlrev_b64 v[68:69], 6, v[230:231]
	v_lshl_add_u64 v[68:69], s[22:23], 0, v[68:69]
	v_lshl_add_u64 v[68:69], s[76:77], 2, v[68:69]
	s_lshl_b32 s92, s6, 2
	v_lshl_add_u64 v[68:69], v[68:69], 0, s[92:93]
	s_waitcnt lgkmcnt(0)
	v_add_f32_e32 v64, v64, v65
	global_store_dword v[68:69], v64, off

; #define LAS __attribute__((address_space(3)))
; __device__ __forceinline__ unsigned cvt_pk_bf16(float lo, float hi) { const cvt_f32x2_t v = {lo, hi}; const cvt_bf16x2_t b = __builtin_convertvector(v, cvt_bf16x2_t); return __builtin_bit_cast(unsigned, b); }
; __device__ __forceinline__ float sq4(f32x4 v) { return (v[0] * v[0] + v[1] * v[1]) + (v[2] * v[2] + v[3] * v[3]); }
;     __device__ __forceinline__ void operator()(const f32x4 (&acc)[2][2][4][2], const Unit& u, int wr, int wc, int fr, int fq) const {
;     ...
; #pragma unroll
;         for (int ai = 0; ai < 2; ++ai) {
;             f32x4 xr[4][2][2];
; #pragma unroll
;             for (int m = 0; m < 4; ++m) { const size_t off = (size_t)(u.pm * 256 + ai * 128 + wr * 64 + m * 16 + fr) * DM + col0;
; #pragma unroll
;                 for (int bj = 0; bj < 2; ++bj)
; #pragma unroll
;                     for (int n = 0; n < 2; ++n) xr[m][bj][n] = *(const f32x4*)(xin + off + 128 * bj + 4 * n); }
;             asm volatile("" ::: "memory");
; #pragma unroll
;             for (int m = 0; m < 4; ++m) {
;                 const int row = u.pm * 256 + ai * 128 + wr * 64 + m * 16 + fr;
;                 const size_t off = (size_t)row * DM + col0;
;                 float ss = 0.f;
; #pragma unroll
;                 for (int bj = 0; bj < 2; ++bj) {
;                     const f32x4 xo0 = xr[m][bj][0] + *(const LAS f32x4*)(gtp + 128 * bj) * acc[ai][bj][m][0], xo1 = xr[m][bj][1] + *(const LAS f32x4*)(gtp + 128 * bj + 4) * acc[ai][bj][m][1];
;                     *(f32x4*)(xout + off + 128 * bj) = xo0; *(f32x4*)(xout + off + 128 * bj + 4) = xo1;
;                     if (gmn) { ss += sq4(xo0) + sq4(xo1); const f32x4 a = xo0 * *(const LAS f32x4*)(gmp + 128 * bj), c = xo1 * *(const LAS f32x4*)(gmp + 128 * bj + 4);
;                         u32x4 w; w.x = cvt_pk_bf16(a[0], a[1]); w.y = cvt_pk_bf16(a[2], a[3]); w.z = cvt_pk_bf16(c[0], c[1]); w.w = cvt_pk_bf16(c[2], c[3]); *(u32x4*)(AX + off + 128 * bj) = w; }
;                 }
;                 if (gmn) { ss += __shfl_xor(ss, 16); ss += __shfl_xor(ss, 32); if (fq == 0) statx[(size_t)row * 16 + u.pn * 4 + wc] = ss; }
;             }
.LBB0_238:
	s_andn2_b64 vcc, exec, s[54:55]
	s_cbranch_vccnz .LBB0_240
	v_pk_fma_f32 v[78:79], v[70:71], v[134:135], v[114:115]
	v_pk_fma_f32 v[74:75], v[66:67], v[130:131], v[106:107]
	ds_write_b128 v208, v[76:79]
	ds_write_b128 v208, v[72:75] offset:16
	ds_read_b128 v[216:219], v210
	ds_read_b128 v[220:223], v210 offset:64
	s_waitcnt lgkmcnt(0)
	global_store_dwordx4 v88, v[216:219], s[20:21] offset:512
	global_store_dwordx4 v88, v[220:223], s[20:21] offset:576
.LBB0_240:
	v_add_u32_e32 v134, 0x80, v226
	v_ashrrev_i32_e32 v135, 31, v134
	s_waitcnt lgkmcnt(0)
	v_lshlrev_b64 v[64:65], 12, v[134:135]
	v_add_u32_e32 v132, 0x90, v226
	v_lshl_add_u64 v[64:65], v[228:229], 0, v[64:65]
	v_ashrrev_i32_e32 v133, 31, v132
	global_load_dwordx4 v[136:139], v[64:65], off offset:16
	global_load_dwordx4 v[140:143], v[64:65], off
	global_load_dwordx4 v[120:123], v[64:65], off offset:528
	global_load_dwordx4 v[124:127], v[64:65], off offset:512
	v_lshlrev_b64 v[64:65], 12, v[132:133]
	v_add_u32_e32 v130, 0xa0, v226
	v_lshl_add_u64 v[64:65], v[228:229], 0, v[64:65]
	v_ashrrev_i32_e32 v131, 31, v130
	global_load_dwordx4 v[112:115], v[64:65], off offset:16
	global_load_dwordx4 v[116:119], v[64:65], off
	global_load_dwordx4 v[104:107], v[64:65], off offset:528
	global_load_dwordx4 v[108:111], v[64:65], off offset:512
	v_lshlrev_b64 v[64:65], 12, v[130:131]
	v_add_u32_e32 v128, 0xb0, v226
	v_lshl_add_u64 v[64:65], v[228:229], 0, v[64:65]
	v_ashrrev_i32_e32 v129, 31, v128
	global_load_dwordx4 v[96:99], v[64:65], off offset:16
	global_load_dwordx4 v[100:103], v[64:65], off
	global_load_dwordx4 v[88:91], v[64:65], off offset:528
	global_load_dwordx4 v[92:95], v[64:65], off offset:512
	v_lshlrev_b64 v[64:65], 12, v[128:129]
	v_lshl_add_u64 v[68:69], v[228:229], 0, v[64:65]
	global_load_dwordx4 v[72:75], v[68:69], off offset:16
	global_load_dwordx4 v[80:83], v[68:69], off
	global_load_dwordx4 v[64:67], v[68:69], off offset:528
	s_nop 0
	global_load_dwordx4 v[68:71], v[68:69], off offset:512
	v_lshlrev_b64 v[76:77], 10, v[134:135]
	v_lshl_add_u64 v[144:145], v[76:77], 0, v[224:225]
	ds_read_b128 v[84:87], v249
	ds_read_b128 v[76:79], v249 offset:16
	s_and_b64 vcc, exec, s[46:47]
	s_waitcnt vmcnt(15) lgkmcnt(0)
	v_pk_fma_f32 v[58:59], v[58:59], v[78:79], v[138:139]
	s_waitcnt vmcnt(14)
	v_pk_fma_f32 v[62:63], v[62:63], v[86:87], v[142:143]
	v_pk_fma_f32 v[60:61], v[60:61], v[84:85], v[140:141]
	v_pk_fma_f32 v[56:57], v[56:57], v[76:77], v[136:137]
	v_lshl_add_u64 v[136:137], v[144:145], 2, s[20:21]
	v_lshl_add_u32 v136, v144, 2, v246
	v_mov_b32_e32 v140, 0
	v_lshl_add_u64 v[138:139], v[144:145], 1, s[16:17]
	v_lshl_add_u64 v[138:139], v[204:205], 0, v[138:139]
	ds_write_b128 v208, v[60:63]
	ds_write_b128 v208, v[56:59] offset:16
	ds_read_b128 v[216:219], v210
	ds_read_b128 v[220:223], v210 offset:64
	s_waitcnt lgkmcnt(0)
	global_store_dwordx4 v136, v[216:219], s[20:21]
	global_store_dwordx4 v136, v[220:223], s[20:21] offset:64
	s_cbranch_vccnz .LBB0_242
	v_mov_b32_e32 v142, v61
	v_mov_b32_e32 v143, v57
	v_mov_b32_e32 v140, v60
	v_mov_b32_e32 v141, v56
	v_pk_mul_f32 v[142:143], v[142:143], v[142:143]
	v_mov_b32_e32 v144, v63
	v_mov_b32_e32 v145, v59
	v_pk_fma_f32 v[140:141], v[140:141], v[140:141], v[142:143]
	v_mov_b32_e32 v142, v62
	v_mov_b32_e32 v143, v58
	v_pk_mul_f32 v[144:145], v[144:145], v[144:145]
	s_nop 0
	v_pk_fma_f32 v[142:143], v[142:143], v[142:143], v[144:145]
	s_nop 0
	v_pk_add_f32 v[140:141], v[140:141], v[142:143]
	ds_read_b128 v[142:145], v192
	ds_read_b128 v[146:149], v192 offset:16
	v_add_f32_e32 v140, v140, v141
	s_waitcnt lgkmcnt(1)
	v_pk_mul_f32 v[62:63], v[62:63], v[144:145]
	v_pk_mul_f32 v[60:61], v[60:61], v[142:143]
	s_waitcnt lgkmcnt(0)
	v_pk_mul_f32 v[142:143], v[58:59], v[148:149]
	v_pk_mul_f32 v[58:59], v[56:57], v[146:147]
	v_cvt_pk_bf16_f32 v56, v60, v61
	v_cvt_pk_bf16_f32 v57, v62, v63
	v_cvt_pk_bf16_f32 v58, v58, v59
	v_cvt_pk_bf16_f32 v59, v142, v143
	ds_bpermute_b32 v56, v206, v56
	ds_bpermute_b32 v57, v206, v57
	ds_bpermute_b32 v58, v206, v58
	ds_bpermute_b32 v59, v206, v59
	s_waitcnt lgkmcnt(0)
	global_store_dwordx4 v[138:139], v[56:59], off
.LBB0_242:
	ds_read_b128 v[60:63], v249 offset:512
	ds_read_b128 v[56:59], v249 offset:528
	s_and_b64 vcc, exec, s[46:47]
	s_waitcnt vmcnt(14) lgkmcnt(1)
	v_pk_fma_f32 v[54:55], v[54:55], v[62:63], v[126:127]
	v_pk_fma_f32 v[52:53], v[52:53], v[60:61], v[124:125]
	s_waitcnt lgkmcnt(0)
	v_pk_fma_f32 v[50:51], v[50:51], v[58:59], v[122:123]
	v_pk_fma_f32 v[48:49], v[48:49], v[56:57], v[120:121]
	ds_write_b128 v208, v[52:55]
	ds_write_b128 v208, v[48:51] offset:16
	ds_read_b128 v[216:219], v210
	ds_read_b128 v[220:223], v210 offset:64
	s_waitcnt lgkmcnt(0)
	global_store_dwordx4 v136, v[216:219], s[20:21] offset:512
	global_store_dwordx4 v136, v[220:223], s[20:21] offset:576
	s_cbranch_vccnz .LBB0_246
	ds_read_b128 v[120:123], v192 offset:512
	ds_read_b128 v[124:127], v192 offset:528
	s_waitcnt lgkmcnt(1)
	v_pk_mul_f32 v[120:121], v[52:53], v[120:121]
	s_waitcnt lgkmcnt(0)
	v_pk_mul_f32 v[124:125], v[48:49], v[124:125]
	v_mul_f32_e32 v49, v49, v49
	v_mul_f32_e32 v53, v53, v53
	v_fmac_f32_e32 v49, v48, v48
	v_mul_f32_e32 v48, v51, v51
	v_pk_mul_f32 v[126:127], v[50:51], v[126:127]
	v_fmac_f32_e32 v53, v52, v52
	v_mul_f32_e32 v52, v55, v55
	v_fmac_f32_e32 v48, v50, v50
	v_and_b32_e32 v50, 64, v242
	v_fmac_f32_e32 v52, v54, v54
	v_add_f32_e32 v48, v49, v48
	v_xor_b32_e32 v49, 16, v242
	v_add_u32_e32 v50, 64, v50
	v_add_f32_e32 v52, v53, v52
	v_cmp_lt_i32_e32 vcc, v49, v50
	v_add_f32_e32 v48, v52, v48
	v_add_f32_e32 v48, v140, v48
	v_cndmask_b32_e32 v49, v242, v49, vcc
	v_lshlrev_b32_e32 v49, 2, v49
	ds_bpermute_b32 v49, v49, v48
	v_pk_mul_f32 v[122:123], v[54:55], v[122:123]
	v_cvt_pk_bf16_f32 v120, v120, v121
	v_cvt_pk_bf16_f32 v121, v122, v123
	v_cvt_pk_bf16_f32 v122, v124, v125
	s_waitcnt lgkmcnt(0)
	v_add_f32_e32 v48, v48, v49
	v_xor_b32_e32 v49, 32, v242
	v_cmp_lt_i32_e32 vcc, v49, v50
	v_cvt_pk_bf16_f32 v123, v126, v127
	ds_bpermute_b32 v120, v206, v120
	ds_bpermute_b32 v121, v206, v121
	ds_bpermute_b32 v122, v206, v122
	ds_bpermute_b32 v123, v206, v123
	s_waitcnt lgkmcnt(0)
	global_store_dwordx4 v[138:139], v[120:123], off offset:256
	v_cndmask_b32_e32 v49, v242, v49, vcc
	v_lshlrev_b32_e32 v49, 2, v49
	ds_bpermute_b32 v49, v49, v48
	s_and_saveexec_b64 s[54:55], s[44:45]
	s_cbranch_execz .LBB0_245
	v_lshlrev_b64 v[50:51], 6, v[134:135]
	v_lshl_add_u64 v[50:51], s[22:23], 0, v[50:51]
	v_lshl_add_u64 v[50:51], s[76:77], 2, v[50:51]
	s_lshl_b32 s92, s6, 2
	v_lshl_add_u64 v[50:51], v[50:51], 0, s[92:93]
	s_waitcnt lgkmcnt(0)
	v_add_f32_e32 v48, v48, v49
	global_store_dword v[50:51], v48, off

; #define LAS __attribute__((address_space(3)))
; __device__ __forceinline__ unsigned cvt_pk_bf16(float lo, float hi) { const cvt_f32x2_t v = {lo, hi}; const cvt_bf16x2_t b = __builtin_convertvector(v, cvt_bf16x2_t); return __builtin_bit_cast(unsigned, b); }
; __device__ __forceinline__ float sq4(f32x4 v) { return (v[0] * v[0] + v[1] * v[1]) + (v[2] * v[2] + v[3] * v[3]); }
;     __device__ __forceinline__ void operator()(const f32x4 (&acc)[2][2][4][2], const Unit& u, int wr, int wc, int fr, int fq) const {
;     ...
; #pragma unroll
;         for (int ai = 0; ai < 2; ++ai) {
;             f32x4 xr[4][2][2];
; #pragma unroll
;             for (int m = 0; m < 4; ++m) { const size_t off = (size_t)(u.pm * 256 + ai * 128 + wr * 64 + m * 16 + fr) * DM + col0;
; #pragma unroll
;                 for (int bj = 0; bj < 2; ++bj)
; #pragma unroll
;                     for (int n = 0; n < 2; ++n) xr[m][bj][n] = *(const f32x4*)(xin + off + 128 * bj + 4 * n); }
;             asm volatile("" ::: "memory");
; #pragma unroll
;             for (int m = 0; m < 4; ++m) {
;                 const int row = u.pm * 256 + ai * 128 + wr * 64 + m * 16 + fr;
;                 const size_t off = (size_t)row * DM + col0;
;                 float ss = 0.f;
; #pragma unroll
;                 for (int bj = 0; bj < 2; ++bj) {
;                     const f32x4 xo0 = xr[m][bj][0] + *(const LAS f32x4*)(gtp + 128 * bj) * acc[ai][bj][m][0], xo1 = xr[m][bj][1] + *(const LAS f32x4*)(gtp + 128 * bj + 4) * acc[ai][bj][m][1];
;                     *(f32x4*)(xout + off + 128 * bj) = xo0; *(f32x4*)(xout + off + 128 * bj + 4) = xo1;
;                     if (gmn) { ss += sq4(xo0) + sq4(xo1); const f32x4 a = xo0 * *(const LAS f32x4*)(gmp + 128 * bj), c = xo1 * *(const LAS f32x4*)(gmp + 128 * bj + 4);
;                         u32x4 w; w.x = cvt_pk_bf16(a[0], a[1]); w.y = cvt_pk_bf16(a[2], a[3]); w.z = cvt_pk_bf16(c[0], c[1]); w.w = cvt_pk_bf16(c[2], c[3]); *(u32x4*)(AX + off + 128 * bj) = w; }
;                 }
;                 if (gmn) { ss += __shfl_xor(ss, 16); ss += __shfl_xor(ss, 32); if (fq == 0) statx[(size_t)row * 16 + u.pn * 4 + wc] = ss; }
;             }
.LBB0_246:
	s_waitcnt lgkmcnt(0)
	v_lshlrev_b64 v[48:49], 10, v[132:133]
	v_lshl_add_u64 v[120:121], v[48:49], 0, v[224:225]
	s_waitcnt vmcnt(14)
	v_pk_fma_f32 v[48:49], v[46:47], v[86:87], v[118:119]
	v_pk_fma_f32 v[46:47], v[44:45], v[84:85], v[116:117]
	v_pk_fma_f32 v[52:53], v[42:43], v[78:79], v[114:115]
	v_pk_fma_f32 v[50:51], v[40:41], v[76:77], v[112:113]
	v_lshl_add_u64 v[54:55], v[120:121], 2, s[20:21]
	v_lshl_add_u32 v54, v120, 2, v246
	s_mov_b64 s[54:55], -1
	s_and_b64 vcc, exec, s[46:47]
	s_waitcnt vmcnt(12)
	v_pk_fma_f32 v[44:45], v[36:37], v[60:61], v[108:109]
	v_pk_fma_f32 v[40:41], v[28:29], v[56:57], v[104:105]
	ds_write_b128 v208, v[46:49]
	ds_write_b128 v208, v[50:53] offset:16
	ds_read_b128 v[216:219], v210
	ds_read_b128 v[220:223], v210 offset:64
	s_waitcnt lgkmcnt(0)
	global_store_dwordx4 v54, v[216:219], s[20:21]
	global_store_dwordx4 v54, v[220:223], s[20:21] offset:64
	s_cbranch_vccnz .LBB0_250
	v_mul_f32_e32 v28, v47, v47
	v_mul_f32_e32 v29, v49, v49
	ds_read_b128 v[112:115], v192
	ds_read_b128 v[116:119], v192 offset:16
	v_fmac_f32_e32 v28, v46, v46
	v_fmac_f32_e32 v29, v48, v48
	v_add_f32_e32 v28, v28, v29
	v_mul_f32_e32 v29, v51, v51
	v_mul_f32_e32 v36, v53, v53
	v_fmac_f32_e32 v29, v50, v50
	v_fmac_f32_e32 v36, v52, v52
	v_add_f32_e32 v29, v29, v36
	v_add_f32_e32 v108, v28, v29
	s_waitcnt lgkmcnt(1)
	v_pk_mul_f32 v[28:29], v[48:49], v[114:115]
	v_pk_mul_f32 v[36:37], v[46:47], v[112:113]
	s_waitcnt lgkmcnt(0)
	v_pk_mul_f32 v[42:43], v[52:53], v[118:119]
	v_pk_mul_f32 v[48:49], v[50:51], v[116:117]
	v_cvt_pk_bf16_f32 v46, v36, v37
	v_cvt_pk_bf16_f32 v47, v28, v29
	v_cvt_pk_bf16_f32 v48, v48, v49
	v_cvt_pk_bf16_f32 v49, v42, v43
	v_lshl_add_u64 v[28:29], v[120:121], 1, s[16:17]
	ds_bpermute_b32 v46, v206, v46
	ds_bpermute_b32 v47, v206, v47
	ds_bpermute_b32 v48, v206, v48
	ds_bpermute_b32 v49, v206, v49
	s_waitcnt lgkmcnt(0)
	v_lshl_add_u64 v[28:29], v[204:205], 0, v[28:29]
	global_store_dwordx4 v[28:29], v[46:49], off
	v_pk_fma_f32 v[42:43], v[30:31], v[58:59], v[106:107]
	s_nop 0
	v_pk_fma_f32 v[46:47], v[38:39], v[62:63], v[110:111]
	ds_write_b128 v208, v[44:47]
	ds_write_b128 v208, v[40:43] offset:16
	ds_read_b128 v[216:219], v210
	ds_read_b128 v[220:223], v210 offset:64
	s_waitcnt lgkmcnt(0)
	global_store_dwordx4 v54, v[216:219], s[20:21] offset:512
	global_store_dwordx4 v54, v[220:223], s[20:21] offset:576
	ds_read_b128 v[48:51], v192 offset:512
	s_waitcnt lgkmcnt(0)
	v_pk_mul_f32 v[36:37], v[46:47], v[50:51]
	v_pk_mul_f32 v[52:53], v[44:45], v[48:49]
	ds_read_b128 v[48:51], v192 offset:528
	s_waitcnt lgkmcnt(0)
	v_pk_mul_f32 v[104:105], v[42:43], v[50:51]
	v_pk_mul_f32 v[50:51], v[40:41], v[48:49]
	v_cvt_pk_bf16_f32 v48, v52, v53
	v_cvt_pk_bf16_f32 v49, v36, v37
	v_cvt_pk_bf16_f32 v50, v50, v51
	v_cvt_pk_bf16_f32 v51, v104, v105
	ds_bpermute_b32 v48, v206, v48
	ds_bpermute_b32 v49, v206, v49
	ds_bpermute_b32 v50, v206, v50
	ds_bpermute_b32 v51, v206, v51
	s_waitcnt lgkmcnt(0)
	global_store_dwordx4 v[28:29], v[48:51], off offset:256
	v_mul_f32_e32 v28, v45, v45
	v_mul_f32_e32 v29, v47, v47
	v_fmac_f32_e32 v28, v44, v44
	v_fmac_f32_e32 v29, v46, v46
	v_add_f32_e32 v28, v28, v29
	v_mul_f32_e32 v29, v41, v41
	v_mul_f32_e32 v36, v43, v43
	v_fmac_f32_e32 v29, v40, v40
	v_fmac_f32_e32 v36, v42, v42
	v_add_f32_e32 v29, v29, v36
	v_and_b32_e32 v36, 64, v242
	v_add_f32_e32 v28, v28, v29
	v_xor_b32_e32 v29, 16, v242
	v_add_u32_e32 v36, 64, v36
	v_cmp_lt_i32_e32 vcc, v29, v36
	v_add_f32_e32 v28, v108, v28
	s_nop 0
	v_cndmask_b32_e32 v29, v242, v29, vcc
	v_lshlrev_b32_e32 v29, 2, v29
	ds_bpermute_b32 v29, v29, v28
	s_waitcnt lgkmcnt(0)
	v_add_f32_e32 v28, v28, v29
	v_xor_b32_e32 v29, 32, v242
	v_cmp_lt_i32_e32 vcc, v29, v36
	s_nop 1
	v_cndmask_b32_e32 v29, v242, v29, vcc
	v_lshlrev_b32_e32 v29, 2, v29
	ds_bpermute_b32 v29, v29, v28
	s_and_saveexec_b64 s[54:55], s[44:45]
	s_cbranch_execz .LBB0_249
	v_lshlrev_b64 v[36:37], 6, v[132:133]
	v_lshl_add_u64 v[36:37], s[22:23], 0, v[36:37]
	v_lshl_add_u64 v[36:37], s[76:77], 2, v[36:37]
	s_lshl_b32 s92, s6, 2
	v_lshl_add_u64 v[36:37], v[36:37], 0, s[92:93]
	s_waitcnt lgkmcnt(0)
	v_add_f32_e32 v28, v28, v29
	global_store_dword v[36:37], v28, off

; #define LAS __attribute__((address_space(3)))
; __device__ __forceinline__ unsigned cvt_pk_bf16(float lo, float hi) { const cvt_f32x2_t v = {lo, hi}; const cvt_bf16x2_t b = __builtin_convertvector(v, cvt_bf16x2_t); return __builtin_bit_cast(unsigned, b); }
; __device__ __forceinline__ float sq4(f32x4 v) { return (v[0] * v[0] + v[1] * v[1]) + (v[2] * v[2] + v[3] * v[3]); }
;     __device__ __forceinline__ void operator()(const f32x4 (&acc)[2][2][4][2], const Unit& u, int wr, int wc, int fr, int fq) const {
;     ...
; #pragma unroll
;         for (int ai = 0; ai < 2; ++ai) {
;             f32x4 xr[4][2][2];
; #pragma unroll
;             for (int m = 0; m < 4; ++m) { const size_t off = (size_t)(u.pm * 256 + ai * 128 + wr * 64 + m * 16 + fr) * DM + col0;
; #pragma unroll
;                 for (int bj = 0; bj < 2; ++bj)
; #pragma unroll
;                     for (int n = 0; n < 2; ++n) xr[m][bj][n] = *(const f32x4*)(xin + off + 128 * bj + 4 * n); }
;             asm volatile("" ::: "memory");
; #pragma unroll
;             for (int m = 0; m < 4; ++m) {
;                 const int row = u.pm * 256 + ai * 128 + wr * 64 + m * 16 + fr;
;                 const size_t off = (size_t)row * DM + col0;
;                 float ss = 0.f;
; #pragma unroll
;                 for (int bj = 0; bj < 2; ++bj) {
;                     const f32x4 xo0 = xr[m][bj][0] + *(const LAS f32x4*)(gtp + 128 * bj) * acc[ai][bj][m][0], xo1 = xr[m][bj][1] + *(const LAS f32x4*)(gtp + 128 * bj + 4) * acc[ai][bj][m][1];
;                     *(f32x4*)(xout + off + 128 * bj) = xo0; *(f32x4*)(xout + off + 128 * bj + 4) = xo1;
;                     if (gmn) { ss += sq4(xo0) + sq4(xo1); const f32x4 a = xo0 * *(const LAS f32x4*)(gmp + 128 * bj), c = xo1 * *(const LAS f32x4*)(gmp + 128 * bj + 4);
;                         u32x4 w; w.x = cvt_pk_bf16(a[0], a[1]); w.y = cvt_pk_bf16(a[2], a[3]); w.z = cvt_pk_bf16(c[0], c[1]); w.w = cvt_pk_bf16(c[2], c[3]); *(u32x4*)(AX + off + 128 * bj) = w; }
;                 }
;                 if (gmn) { ss += __shfl_xor(ss, 16); ss += __shfl_xor(ss, 32); if (fq == 0) statx[(size_t)row * 16 + u.pn * 4 + wc] = ss; }
;             }
.LBB0_250:
	s_andn2_b64 vcc, exec, s[54:55]
	s_cbranch_vccnz .LBB0_252
	v_pk_fma_f32 v[46:47], v[38:39], v[62:63], v[110:111]
	v_pk_fma_f32 v[42:43], v[30:31], v[58:59], v[106:107]
	ds_write_b128 v208, v[44:47]
	ds_write_b128 v208, v[40:43] offset:16
	ds_read_b128 v[216:219], v210
	ds_read_b128 v[220:223], v210 offset:64
	s_waitcnt lgkmcnt(0)
	global_store_dwordx4 v54, v[216:219], s[20:21] offset:512
	global_store_dwordx4 v54, v[220:223], s[20:21] offset:576
.LBB0_252:
	s_waitcnt lgkmcnt(0)
	v_lshlrev_b64 v[28:29], 10, v[130:131]
	v_lshl_add_u64 v[30:31], v[28:29], 0, v[224:225]
	s_waitcnt vmcnt(12)
	v_pk_fma_f32 v[34:35], v[34:35], v[86:87], v[102:103]
	v_pk_fma_f32 v[32:33], v[32:33], v[84:85], v[100:101]
	v_pk_fma_f32 v[38:39], v[26:27], v[78:79], v[98:99]
	v_pk_fma_f32 v[36:37], v[24:25], v[76:77], v[96:97]
	v_lshl_add_u64 v[40:41], v[30:31], 2, s[20:21]
	v_lshl_add_u32 v40, v30, 2, v246
	s_mov_b64 s[54:55], -1
	s_and_b64 vcc, exec, s[46:47]
	s_waitcnt vmcnt(10)
	v_pk_fma_f32 v[28:29], v[20:21], v[60:61], v[92:93]
	v_pk_fma_f32 v[24:25], v[12:13], v[56:57], v[88:89]
	ds_write_b128 v208, v[32:35]
	ds_write_b128 v208, v[36:39] offset:16
	ds_read_b128 v[216:219], v210
	ds_read_b128 v[220:223], v210 offset:64
	s_waitcnt lgkmcnt(0)
	global_store_dwordx4 v40, v[216:219], s[20:21]
	global_store_dwordx4 v40, v[220:223], s[20:21] offset:64
	s_cbranch_vccnz .LBB0_256
	v_mul_f32_e32 v12, v33, v33
	v_mul_f32_e32 v13, v35, v35
	ds_read_b128 v[42:45], v192
	ds_read_b128 v[46:49], v192 offset:16
	v_fmac_f32_e32 v12, v32, v32
	v_fmac_f32_e32 v13, v34, v34
	v_add_f32_e32 v12, v12, v13
	v_mul_f32_e32 v13, v37, v37
	v_mul_f32_e32 v20, v39, v39
	v_fmac_f32_e32 v13, v36, v36
	v_fmac_f32_e32 v20, v38, v38
	v_add_f32_e32 v13, v13, v20
	v_add_f32_e32 v50, v12, v13
	s_waitcnt lgkmcnt(1)
	v_pk_mul_f32 v[12:13], v[34:35], v[44:45]
	v_pk_mul_f32 v[20:21], v[32:33], v[42:43]
	s_waitcnt lgkmcnt(0)
	v_pk_mul_f32 v[26:27], v[38:39], v[48:49]
	v_pk_mul_f32 v[34:35], v[36:37], v[46:47]
	v_cvt_pk_bf16_f32 v32, v20, v21
	v_cvt_pk_bf16_f32 v33, v12, v13
	v_cvt_pk_bf16_f32 v34, v34, v35
	v_cvt_pk_bf16_f32 v35, v26, v27
	v_lshl_add_u64 v[12:13], v[30:31], 1, s[16:17]
	v_lshl_add_u64 v[12:13], v[204:205], 0, v[12:13]
	v_pk_fma_f32 v[30:31], v[22:23], v[62:63], v[94:95]
	ds_bpermute_b32 v32, v206, v32
	ds_bpermute_b32 v33, v206, v33
	ds_bpermute_b32 v34, v206, v34
	ds_bpermute_b32 v35, v206, v35
	s_waitcnt lgkmcnt(0)
	global_store_dwordx4 v[12:13], v[32:35], off
	v_pk_fma_f32 v[26:27], v[14:15], v[58:59], v[90:91]
	ds_write_b128 v208, v[28:31]
	ds_write_b128 v208, v[24:27] offset:16
	ds_read_b128 v[216:219], v210
	ds_read_b128 v[220:223], v210 offset:64
	s_waitcnt lgkmcnt(0)
	global_store_dwordx4 v40, v[216:219], s[20:21] offset:512
	global_store_dwordx4 v40, v[220:223], s[20:21] offset:576
	ds_read_b128 v[32:35], v192 offset:512
	s_waitcnt lgkmcnt(0)
	v_pk_mul_f32 v[20:21], v[30:31], v[34:35]
	v_pk_mul_f32 v[36:37], v[28:29], v[32:33]
	ds_read_b128 v[32:35], v192 offset:528
	s_waitcnt lgkmcnt(0)
	v_pk_mul_f32 v[38:39], v[26:27], v[34:35]
	v_pk_mul_f32 v[34:35], v[24:25], v[32:33]
	v_cvt_pk_bf16_f32 v32, v36, v37
	v_cvt_pk_bf16_f32 v33, v20, v21
	v_cvt_pk_bf16_f32 v34, v34, v35
	v_cvt_pk_bf16_f32 v35, v38, v39
	ds_bpermute_b32 v32, v206, v32
	ds_bpermute_b32 v33, v206, v33
	ds_bpermute_b32 v34, v206, v34
	ds_bpermute_b32 v35, v206, v35
	s_waitcnt lgkmcnt(0)
	global_store_dwordx4 v[12:13], v[32:35], off offset:256
	v_mul_f32_e32 v12, v29, v29
	v_mul_f32_e32 v13, v31, v31
	v_fmac_f32_e32 v12, v28, v28
	v_fmac_f32_e32 v13, v30, v30
	v_add_f32_e32 v12, v12, v13
	v_mul_f32_e32 v13, v25, v25
	v_mul_f32_e32 v20, v27, v27
	v_fmac_f32_e32 v13, v24, v24
	v_fmac_f32_e32 v20, v26, v26
	v_add_f32_e32 v13, v13, v20
	v_and_b32_e32 v20, 64, v242
	v_add_f32_e32 v12, v12, v13
	v_xor_b32_e32 v13, 16, v242
	v_add_u32_e32 v20, 64, v20
	v_cmp_lt_i32_e32 vcc, v13, v20
	v_add_f32_e32 v12, v50, v12
	s_nop 0
	v_cndmask_b32_e32 v13, v242, v13, vcc
	v_lshlrev_b32_e32 v13, 2, v13
	ds_bpermute_b32 v13, v13, v12
	s_waitcnt lgkmcnt(0)
	v_add_f32_e32 v12, v12, v13
	v_xor_b32_e32 v13, 32, v242
	v_cmp_lt_i32_e32 vcc, v13, v20
	s_nop 1
	v_cndmask_b32_e32 v13, v242, v13, vcc
	v_lshlrev_b32_e32 v13, 2, v13
	ds_bpermute_b32 v13, v13, v12
	s_and_saveexec_b64 s[54:55], s[44:45]
	s_cbranch_execz .LBB0_255
	v_lshlrev_b64 v[20:21], 6, v[130:131]
	v_lshl_add_u64 v[20:21], s[22:23], 0, v[20:21]
	v_lshl_add_u64 v[20:21], s[76:77], 2, v[20:21]
	s_lshl_b32 s92, s6, 2
	v_lshl_add_u64 v[20:21], v[20:21], 0, s[92:93]
	s_waitcnt lgkmcnt(0)
	v_add_f32_e32 v12, v12, v13
	global_store_dword v[20:21], v12, off

; #define LAS __attribute__((address_space(3)))
; __device__ __forceinline__ unsigned cvt_pk_bf16(float lo, float hi) { const cvt_f32x2_t v = {lo, hi}; const cvt_bf16x2_t b = __builtin_convertvector(v, cvt_bf16x2_t); return __builtin_bit_cast(unsigned, b); }
; __device__ __forceinline__ float sq4(f32x4 v) { return (v[0] * v[0] + v[1] * v[1]) + (v[2] * v[2] + v[3] * v[3]); }
;     __device__ __forceinline__ void operator()(const f32x4 (&acc)[2][2][4][2], const Unit& u, int wr, int wc, int fr, int fq) const {
;     ...
; #pragma unroll
;         for (int ai = 0; ai < 2; ++ai) {
;             f32x4 xr[4][2][2];
; #pragma unroll
;             for (int m = 0; m < 4; ++m) { const size_t off = (size_t)(u.pm * 256 + ai * 128 + wr * 64 + m * 16 + fr) * DM + col0;
; #pragma unroll
;                 for (int bj = 0; bj < 2; ++bj)
; #pragma unroll
;                     for (int n = 0; n < 2; ++n) xr[m][bj][n] = *(const f32x4*)(xin + off + 128 * bj + 4 * n); }
;             asm volatile("" ::: "memory");
; #pragma unroll
;             for (int m = 0; m < 4; ++m) {
;                 const int row = u.pm * 256 + ai * 128 + wr * 64 + m * 16 + fr;
;                 const size_t off = (size_t)row * DM + col0;
;                 float ss = 0.f;
; #pragma unroll
;                 for (int bj = 0; bj < 2; ++bj) {
;                     const f32x4 xo0 = xr[m][bj][0] + *(const LAS f32x4*)(gtp + 128 * bj) * acc[ai][bj][m][0], xo1 = xr[m][bj][1] + *(const LAS f32x4*)(gtp + 128 * bj + 4) * acc[ai][bj][m][1];
;                     *(f32x4*)(xout + off + 128 * bj) = xo0; *(f32x4*)(xout + off + 128 * bj + 4) = xo1;
;                     if (gmn) { ss += sq4(xo0) + sq4(xo1); const f32x4 a = xo0 * *(const LAS f32x4*)(gmp + 128 * bj), c = xo1 * *(const LAS f32x4*)(gmp + 128 * bj + 4);
;                         u32x4 w; w.x = cvt_pk_bf16(a[0], a[1]); w.y = cvt_pk_bf16(a[2], a[3]); w.z = cvt_pk_bf16(c[0], c[1]); w.w = cvt_pk_bf16(c[2], c[3]); *(u32x4*)(AX + off + 128 * bj) = w; }
;                 }
;                 if (gmn) { ss += __shfl_xor(ss, 16); ss += __shfl_xor(ss, 32); if (fq == 0) statx[(size_t)row * 16 + u.pn * 4 + wc] = ss; }
;             }
.LBB0_256:
	s_andn2_b64 vcc, exec, s[54:55]
	s_cbranch_vccnz .LBB0_258
	v_pk_fma_f32 v[30:31], v[22:23], v[62:63], v[94:95]
	v_pk_fma_f32 v[26:27], v[14:15], v[58:59], v[90:91]
	ds_write_b128 v208, v[28:31]
	ds_write_b128 v208, v[24:27] offset:16
	ds_read_b128 v[216:219], v210
	ds_read_b128 v[220:223], v210 offset:64
	s_waitcnt lgkmcnt(0)
	global_store_dwordx4 v40, v[216:219], s[20:21] offset:512
	global_store_dwordx4 v40, v[220:223], s[20:21] offset:576
.LBB0_258:
	s_waitcnt lgkmcnt(0)
	v_lshlrev_b64 v[12:13], 10, v[128:129]
	v_lshl_add_u64 v[14:15], v[12:13], 0, v[224:225]
	s_waitcnt vmcnt(10)
	v_pk_fma_f32 v[18:19], v[18:19], v[86:87], v[82:83]
	v_pk_fma_f32 v[16:17], v[16:17], v[84:85], v[80:81]
	v_pk_fma_f32 v[22:23], v[10:11], v[78:79], v[74:75]
	v_pk_fma_f32 v[20:21], v[8:9], v[76:77], v[72:73]
	v_lshl_add_u64 v[24:25], v[14:15], 2, s[20:21]
	v_lshl_add_u32 v24, v14, 2, v246
	s_mov_b64 s[54:55], -1
	s_and_b64 vcc, exec, s[46:47]
	s_waitcnt vmcnt(8)
	v_pk_fma_f32 v[12:13], v[4:5], v[60:61], v[68:69]
	v_pk_fma_f32 v[8:9], v[0:1], v[56:57], v[64:65]
	ds_write_b128 v208, v[16:19]
	ds_write_b128 v208, v[20:23] offset:16
	ds_read_b128 v[216:219], v210
	ds_read_b128 v[220:223], v210 offset:64
	s_waitcnt lgkmcnt(0)
	global_store_dwordx4 v24, v[216:219], s[20:21]
	global_store_dwordx4 v24, v[220:223], s[20:21] offset:64
	s_cbranch_vccz .LBB0_265
	s_andn2_b64 vcc, exec, s[54:55]
	s_cbranch_vccz .LBB0_268
.LBB0_260:
	ds_read_b32 v216, v252
	ds_read_b32 v218, v252 offset:256
	ds_read_b32 v220, v252 offset:512
	ds_read_b32 v222, v252 offset:768
	v_mov_b32_e32 v217, v193
	v_mov_b32_e32 v219, v193
	v_mov_b32_e32 v221, v193
	v_mov_b32_e32 v223, v193
	s_waitcnt lgkmcnt(0)
	s_andn2_b64 vcc, exec, s[42:43]
	s_mov_b64 s[42:43], -1
	s_cbranch_vccnz .LBB0_201
	s_branch .LBB0_269

; #define LAS __attribute__((address_space(3)))
; __device__ __forceinline__ unsigned cvt_pk_bf16(float lo, float hi) { const cvt_f32x2_t v = {lo, hi}; const cvt_bf16x2_t b = __builtin_convertvector(v, cvt_bf16x2_t); return __builtin_bit_cast(unsigned, b); }
; __device__ __forceinline__ float sq4(f32x4 v) { return (v[0] * v[0] + v[1] * v[1]) + (v[2] * v[2] + v[3] * v[3]); }
;     __device__ __forceinline__ void operator()(const f32x4 (&acc)[2][2][4][2], const Unit& u, int wr, int wc, int fr, int fq) const {
;     ...
; #pragma unroll
;         for (int ai = 0; ai < 2; ++ai) {
;             f32x4 xr[4][2][2];
; #pragma unroll
;             for (int m = 0; m < 4; ++m) { const size_t off = (size_t)(u.pm * 256 + ai * 128 + wr * 64 + m * 16 + fr) * DM + col0;
; #pragma unroll
;                 for (int bj = 0; bj < 2; ++bj)
; #pragma unroll
;                     for (int n = 0; n < 2; ++n) xr[m][bj][n] = *(const f32x4*)(xin + off + 128 * bj + 4 * n); }
;             asm volatile("" ::: "memory");
; #pragma unroll
;             for (int m = 0; m < 4; ++m) {
;                 const int row = u.pm * 256 + ai * 128 + wr * 64 + m * 16 + fr;
;                 const size_t off = (size_t)row * DM + col0;
;                 float ss = 0.f;
; #pragma unroll
;                 for (int bj = 0; bj < 2; ++bj) {
;                     const f32x4 xo0 = xr[m][bj][0] + *(const LAS f32x4*)(gtp + 128 * bj) * acc[ai][bj][m][0], xo1 = xr[m][bj][1] + *(const LAS f32x4*)(gtp + 128 * bj + 4) * acc[ai][bj][m][1];
;                     *(f32x4*)(xout + off + 128 * bj) = xo0; *(f32x4*)(xout + off + 128 * bj + 4) = xo1;
;                     if (gmn) { ss += sq4(xo0) + sq4(xo1); const f32x4 a = xo0 * *(const LAS f32x4*)(gmp + 128 * bj), c = xo1 * *(const LAS f32x4*)(gmp + 128 * bj + 4);
;                         u32x4 w; w.x = cvt_pk_bf16(a[0], a[1]); w.y = cvt_pk_bf16(a[2], a[3]); w.z = cvt_pk_bf16(c[0], c[1]); w.w = cvt_pk_bf16(c[2], c[3]); *(u32x4*)(AX + off + 128 * bj) = w; }
;                 }
;                 if (gmn) { ss += __shfl_xor(ss, 16); ss += __shfl_xor(ss, 32); if (fq == 0) statx[(size_t)row * 16 + u.pn * 4 + wc] = ss; }
;             }
.LBB0_265:
	v_mul_f32_e32 v0, v17, v17
	v_mul_f32_e32 v1, v19, v19
	ds_read_b128 v[26:29], v192
	ds_read_b128 v[30:33], v192 offset:16
	v_fmac_f32_e32 v0, v16, v16
	v_fmac_f32_e32 v1, v18, v18
	v_add_f32_e32 v0, v0, v1
	v_mul_f32_e32 v1, v21, v21
	v_mul_f32_e32 v4, v23, v23
	v_fmac_f32_e32 v1, v20, v20
	v_fmac_f32_e32 v4, v22, v22
	v_add_f32_e32 v1, v1, v4
	v_add_f32_e32 v34, v0, v1
	s_waitcnt lgkmcnt(1)
	v_pk_mul_f32 v[0:1], v[18:19], v[28:29]
	v_pk_mul_f32 v[4:5], v[16:17], v[26:27]
	s_waitcnt lgkmcnt(0)
	v_pk_mul_f32 v[10:11], v[22:23], v[32:33]
	v_pk_mul_f32 v[18:19], v[20:21], v[30:31]
	v_cvt_pk_bf16_f32 v16, v4, v5
	v_cvt_pk_bf16_f32 v17, v0, v1
	v_cvt_pk_bf16_f32 v18, v18, v19
	v_cvt_pk_bf16_f32 v19, v10, v11
	v_lshl_add_u64 v[0:1], v[14:15], 1, s[16:17]
	v_lshl_add_u64 v[0:1], v[204:205], 0, v[0:1]
	v_pk_fma_f32 v[14:15], v[6:7], v[62:63], v[70:71]
	ds_bpermute_b32 v16, v206, v16
	ds_bpermute_b32 v17, v206, v17
	ds_bpermute_b32 v18, v206, v18
	ds_bpermute_b32 v19, v206, v19
	s_waitcnt lgkmcnt(0)
	global_store_dwordx4 v[0:1], v[16:19], off
	v_pk_fma_f32 v[10:11], v[2:3], v[58:59], v[66:67]
	ds_write_b128 v208, v[12:15]
	ds_write_b128 v208, v[8:11] offset:16
	ds_read_b128 v[216:219], v210
	ds_read_b128 v[220:223], v210 offset:64
	s_waitcnt lgkmcnt(0)
	global_store_dwordx4 v24, v[216:219], s[20:21] offset:512
	global_store_dwordx4 v24, v[220:223], s[20:21] offset:576
	ds_read_b128 v[16:19], v192 offset:512
	s_waitcnt lgkmcnt(0)
	v_pk_mul_f32 v[4:5], v[14:15], v[18:19]
	v_pk_mul_f32 v[20:21], v[12:13], v[16:17]
	ds_read_b128 v[16:19], v192 offset:528
	s_waitcnt lgkmcnt(0)
	v_pk_mul_f32 v[22:23], v[10:11], v[18:19]
	v_pk_mul_f32 v[18:19], v[8:9], v[16:17]
	v_cvt_pk_bf16_f32 v16, v20, v21
	v_cvt_pk_bf16_f32 v17, v4, v5
	v_cvt_pk_bf16_f32 v18, v18, v19
	v_cvt_pk_bf16_f32 v19, v22, v23
	ds_bpermute_b32 v16, v206, v16
	ds_bpermute_b32 v17, v206, v17
	ds_bpermute_b32 v18, v206, v18
	ds_bpermute_b32 v19, v206, v19
	s_waitcnt lgkmcnt(0)
	global_store_dwordx4 v[0:1], v[16:19], off offset:256
	v_mul_f32_e32 v0, v13, v13
	v_mul_f32_e32 v1, v15, v15
	v_fmac_f32_e32 v0, v12, v12
	v_fmac_f32_e32 v1, v14, v14
	v_add_f32_e32 v0, v0, v1
	v_mul_f32_e32 v1, v9, v9
	v_mul_f32_e32 v4, v11, v11
	v_fmac_f32_e32 v1, v8, v8
	v_fmac_f32_e32 v4, v10, v10
	v_add_f32_e32 v1, v1, v4
	v_and_b32_e32 v4, 64, v242
	v_add_f32_e32 v0, v0, v1
	v_xor_b32_e32 v1, 16, v242
	v_add_u32_e32 v4, 64, v4
	v_cmp_lt_i32_e32 vcc, v1, v4
	v_add_f32_e32 v0, v34, v0
	s_nop 0
	v_cndmask_b32_e32 v1, v242, v1, vcc
	v_lshlrev_b32_e32 v1, 2, v1
	ds_bpermute_b32 v1, v1, v0
	s_waitcnt lgkmcnt(0)
	v_add_f32_e32 v0, v0, v1
	v_xor_b32_e32 v1, 32, v242
	v_cmp_lt_i32_e32 vcc, v1, v4
	s_nop 1
	v_cndmask_b32_e32 v1, v242, v1, vcc
	v_lshlrev_b32_e32 v1, 2, v1
	ds_bpermute_b32 v1, v1, v0
	s_and_saveexec_b64 s[46:47], s[44:45]
	s_cbranch_execz .LBB0_267
	v_lshlrev_b64 v[4:5], 6, v[128:129]
	v_lshl_add_u64 v[4:5], s[22:23], 0, v[4:5]
	v_lshl_add_u64 v[4:5], s[76:77], 2, v[4:5]
	s_lshl_b32 s92, s6, 2
	v_lshl_add_u64 v[4:5], v[4:5], 0, s[92:93]
	s_waitcnt lgkmcnt(0)
	v_add_f32_e32 v0, v0, v1
	global_store_dword v[4:5], v0, off

; #define LAS __attribute__((address_space(3)))
; __device__ __forceinline__ unsigned cvt_pk_bf16(float lo, float hi) { const cvt_f32x2_t v = {lo, hi}; const cvt_bf16x2_t b = __builtin_convertvector(v, cvt_bf16x2_t); return __builtin_bit_cast(unsigned, b); }
; __device__ __forceinline__ float sq4(f32x4 v) { return (v[0] * v[0] + v[1] * v[1]) + (v[2] * v[2] + v[3] * v[3]); }
;     __device__ __forceinline__ void operator()(const f32x4 (&acc)[2][2][4][2], const Unit& u, int wr, int wc, int fr, int fq) const {
;     ...
; #pragma unroll
;         for (int ai = 0; ai < 2; ++ai) {
;             f32x4 xr[4][2][2];
; #pragma unroll
;             for (int m = 0; m < 4; ++m) { const size_t off = (size_t)(u.pm * 256 + ai * 128 + wr * 64 + m * 16 + fr) * DM + col0;
; #pragma unroll
;                 for (int bj = 0; bj < 2; ++bj)
; #pragma unroll
;                     for (int n = 0; n < 2; ++n) xr[m][bj][n] = *(const f32x4*)(xin + off + 128 * bj + 4 * n); }
;             asm volatile("" ::: "memory");
; #pragma unroll
;             for (int m = 0; m < 4; ++m) {
;                 const int row = u.pm * 256 + ai * 128 + wr * 64 + m * 16 + fr;
;                 const size_t off = (size_t)row * DM + col0;
;                 float ss = 0.f;
; #pragma unroll
;                 for (int bj = 0; bj < 2; ++bj) {
;                     const f32x4 xo0 = xr[m][bj][0] + *(const LAS f32x4*)(gtp + 128 * bj) * acc[ai][bj][m][0], xo1 = xr[m][bj][1] + *(const LAS f32x4*)(gtp + 128 * bj + 4) * acc[ai][bj][m][1];
;                     *(f32x4*)(xout + off + 128 * bj) = xo0; *(f32x4*)(xout + off + 128 * bj + 4) = xo1;
;                     if (gmn) { ss += sq4(xo0) + sq4(xo1); const f32x4 a = xo0 * *(const LAS f32x4*)(gmp + 128 * bj), c = xo1 * *(const LAS f32x4*)(gmp + 128 * bj + 4);
;                         u32x4 w; w.x = cvt_pk_bf16(a[0], a[1]); w.y = cvt_pk_bf16(a[2], a[3]); w.z = cvt_pk_bf16(c[0], c[1]); w.w = cvt_pk_bf16(c[2], c[3]); *(u32x4*)(AX + off + 128 * bj) = w; }
;                 }
;                 if (gmn) { ss += __shfl_xor(ss, 16); ss += __shfl_xor(ss, 32); if (fq == 0) statx[(size_t)row * 16 + u.pn * 4 + wc] = ss; }
;             }
.LBB0_268:
	v_pk_fma_f32 v[14:15], v[6:7], v[62:63], v[70:71]
	v_pk_fma_f32 v[10:11], v[2:3], v[58:59], v[66:67]
	ds_write_b128 v208, v[12:15]
	ds_write_b128 v208, v[8:11] offset:16
	ds_read_b128 v[216:219], v210
	ds_read_b128 v[220:223], v210 offset:64
	s_waitcnt lgkmcnt(0)
	global_store_dwordx4 v24, v[216:219], s[20:21] offset:512
	global_store_dwordx4 v24, v[220:223], s[20:21] offset:576
	ds_read_b32 v216, v252
	ds_read_b32 v218, v252 offset:256
	ds_read_b32 v220, v252 offset:512
	ds_read_b32 v222, v252 offset:768
	v_mov_b32_e32 v217, v193
	v_mov_b32_e32 v219, v193
	v_mov_b32_e32 v221, v193
	v_mov_b32_e32 v223, v193
	s_waitcnt lgkmcnt(0)
	s_andn2_b64 vcc, exec, s[42:43]
	s_mov_b64 s[42:43], -1
	s_cbranch_vccnz .LBB0_201

; #define LAS __attribute__((address_space(3)))
;     __device__ __forceinline__ void operator()(const f32x4 (&acc)[2][2][4][2], const Unit& u, int wr, int wc, int fr, int fq) const {
;         const int b = u.pm >> 3, col0 = u.pn * 256 + wc * 32 + 8 * fq;
;         { const int t = (wr * 4 + wc) * 64 + fq * 16 + fr;
;           if (t < 64) ((LAS f32x4*)gl)[t] = *(const f32x4*)(gate + (size_t)b * gate_ld + u.pn * 256 + 4 * t);
;           else if (t < 128 && gmn) ((LAS f32x4*)gl)[t] = *(const f32x4*)(gmn + (size_t)b * DM + u.pn * 256 + 4 * (t - 64));
;           asm volatile("s_waitcnt vmcnt(0) lgkmcnt(0)" ::: "memory"); __builtin_amdgcn_s_barrier(); asm volatile("" ::: "memory"); }
.LBB0_319:
	s_mul_i32 s100, s40, 36
	s_add_i32 s100, s100, 0x24000
	s_cmp_eq_u32 s40, 0x1c0
	s_cselect_b32 s100, 0x20c00, s100
	s_lshl_b32 s101, s40, 4
	s_add_i32 s101, s101, 0x21800
	v_lshrrev_b32_e32 v210, 2, v242
	v_and_b32_e32 v246, 3, v242
	v_mul_u32_u24_e32 v210, 0x90, v210
	v_lshl_add_u32 v210, v246, 4, v210
	v_add_u32_e32 v210, s100, v210
	v_mul_u32_u24_e32 v208, 0x90, v211
	v_lshl_add_u32 v208, v207, 5, v208
	v_add_u32_e32 v208, s100, v208
	v_lshrrev_b32_e32 v252, 2, v242
	v_sub_u32_e32 v252, v252, v211
	v_lshlrev_b32_e32 v252, 12, v252
	v_lshl_add_u32 v246, v246, 4, v252
	v_lshlrev_b32_e32 v252, 5, v207
	v_sub_u32_e32 v246, v246, v252
	v_lshl_add_u32 v252, v242, 2, s101
	ds_write_b32 v252, v216
	ds_write_b32 v252, v218 offset:256
	ds_write_b32 v252, v220 offset:512
	ds_write_b32 v252, v222 offset:768
	v_and_b32_e32 v206, 3, v242
	v_lshrrev_b32_e32 v204, 2, v242
	v_lshl_add_u32 v205, v206, 4, v204
	v_sub_u32_e32 v204, v204, v211
	v_sub_u32_e32 v206, v206, v207
	v_lshlrev_b32_e32 v204, 11, v204
	v_lshl_add_u32 v204, v206, 4, v204
	v_lshlrev_b32_e32 v206, 2, v205
	v_ashrrev_i32_e32 v205, 31, v204
	v_mov_b32_e32 v106, v211
	v_mov_b32_e32 v250, v207
	s_ashr_i32 s46, s77, 3
	v_lshlrev_b32_e32 v104, 4, v250
	v_add3_u32 v107, s40, v106, v104
	s_lshl_b32 s44, s76, 8
	v_cmp_lt_i32_e32 vcc, 63, v107
	s_mov_b64 s[56:57], 0
	s_and_saveexec_b64 s[54:55], vcc
	s_xor_b64 s[54:55], exec, s[54:55]
	s_movk_i32 s63, 0x5ff
	s_cbranch_execnz .LBB0_368
	s_andn2_saveexec_b64 s[54:55], s[54:55]
	s_cbranch_execnz .LBB0_371

; #define LAS __attribute__((address_space(3)))
; __device__ __forceinline__ unsigned cvt_pk_bf16(float lo, float hi) { const cvt_f32x2_t v = {lo, hi}; const cvt_bf16x2_t b = __builtin_convertvector(v, cvt_bf16x2_t); return __builtin_bit_cast(unsigned, b); }
; __device__ __forceinline__ float sq4(f32x4 v) { return (v[0] * v[0] + v[1] * v[1]) + (v[2] * v[2] + v[3] * v[3]); }
;     __device__ __forceinline__ void operator()(const f32x4 (&acc)[2][2][4][2], const Unit& u, int wr, int wc, int fr, int fq) const {
;     ...
; #pragma unroll
;         for (int ai = 0; ai < 2; ++ai) {
;             f32x4 xr[4][2][2];
; #pragma unroll
;             for (int m = 0; m < 4; ++m) { const size_t off = (size_t)(u.pm * 256 + ai * 128 + wr * 64 + m * 16 + fr) * DM + col0;
; #pragma unroll
;                 for (int bj = 0; bj < 2; ++bj)
; #pragma unroll
;                     for (int n = 0; n < 2; ++n) xr[m][bj][n] = *(const f32x4*)(xin + off + 128 * bj + 4 * n); }
;             asm volatile("" ::: "memory");
; #pragma unroll
;             for (int m = 0; m < 4; ++m) {
;                 const int row = u.pm * 256 + ai * 128 + wr * 64 + m * 16 + fr;
;                 const size_t off = (size_t)row * DM + col0;
;                 float ss = 0.f;
; #pragma unroll
;                 for (int bj = 0; bj < 2; ++bj) {
;                     const f32x4 xo0 = xr[m][bj][0] + *(const LAS f32x4*)(gtp + 128 * bj) * acc[ai][bj][m][0], xo1 = xr[m][bj][1] + *(const LAS f32x4*)(gtp + 128 * bj + 4) * acc[ai][bj][m][1];
;                     *(f32x4*)(xout + off + 128 * bj) = xo0; *(f32x4*)(xout + off + 128 * bj + 4) = xo1;
;                     if (gmn) { ss += sq4(xo0) + sq4(xo1); const f32x4 a = xo0 * *(const LAS f32x4*)(gmp + 128 * bj), c = xo1 * *(const LAS f32x4*)(gmp + 128 * bj + 4);
;                         u32x4 w; w.x = cvt_pk_bf16(a[0], a[1]); w.y = cvt_pk_bf16(a[2], a[3]); w.z = cvt_pk_bf16(c[0], c[1]); w.w = cvt_pk_bf16(c[2], c[3]); *(u32x4*)(AX + off + 128 * bj) = w; }
;                 }
;                 if (gmn) { ss += __shfl_xor(ss, 16); ss += __shfl_xor(ss, 32); if (fq == 0) statx[(size_t)row * 16 + u.pn * 4 + wc] = ss; }
;             }
.LBB0_323:
	s_or_b64 exec, exec, s[46:47]
	s_or_b32 s44, s44, s9
	v_lshl_add_u32 v224, v250, 3, s44
	s_lshl_b32 s44, s77, 8
	s_add_i32 s44, s44, s8
	v_add_u32_e32 v226, s44, v106
	v_readlane_b32 s44, v255, 48
	v_lshlrev_b32_e32 v104, 5, v250
	v_ashrrev_i32_e32 v225, 31, v224
	v_readlane_b32 s45, v255, 49
	v_ashrrev_i32_e32 v227, 31, v226
	v_add_u32_e32 v249, s41, v104
	v_add_u32_e32 v192, s4, v104
	v_lshl_add_u64 v[228:229], v[224:225], 2, s[44:45]
	v_lshlrev_b64 v[104:105], 12, v[226:227]
	v_add_u32_e32 v234, 16, v226
	s_waitcnt vmcnt(0) lgkmcnt(0)
	s_barrier
	v_lshl_add_u64 v[104:105], v[228:229], 0, v[104:105]
	v_ashrrev_i32_e32 v235, 31, v234
	global_load_dwordx4 v[194:197], v[104:105], off offset:16
	global_load_dwordx4 v[198:201], v[104:105], off
	global_load_dwordx4 v[184:187], v[104:105], off offset:528
	global_load_dwordx4 v[188:191], v[104:105], off offset:512
	v_lshlrev_b64 v[104:105], 12, v[234:235]
	v_add_u32_e32 v232, 32, v226
	v_lshl_add_u64 v[104:105], v[228:229], 0, v[104:105]
	v_ashrrev_i32_e32 v233, 31, v232
	global_load_dwordx4 v[176:179], v[104:105], off offset:16
	global_load_dwordx4 v[180:183], v[104:105], off
	global_load_dwordx4 v[168:171], v[104:105], off offset:528
	global_load_dwordx4 v[172:175], v[104:105], off offset:512
	v_lshlrev_b64 v[104:105], 12, v[232:233]
	v_add_u32_e32 v230, 48, v226
	v_lshl_add_u64 v[104:105], v[228:229], 0, v[104:105]
	v_ashrrev_i32_e32 v231, 31, v230
	global_load_dwordx4 v[160:163], v[104:105], off offset:16
	global_load_dwordx4 v[164:167], v[104:105], off
	global_load_dwordx4 v[152:155], v[104:105], off offset:528
	global_load_dwordx4 v[156:159], v[104:105], off offset:512
	v_lshlrev_b64 v[104:105], 12, v[230:231]
	v_lshl_add_u64 v[112:113], v[228:229], 0, v[104:105]
	global_load_dwordx4 v[136:139], v[112:113], off offset:16
	global_load_dwordx4 v[144:147], v[112:113], off
	global_load_dwordx4 v[104:107], v[112:113], off offset:528
	s_nop 0
	global_load_dwordx4 v[112:115], v[112:113], off offset:512
	v_lshlrev_b64 v[140:141], 10, v[226:227]
	v_lshl_add_u64 v[202:203], v[140:141], 0, v[224:225]
	ds_read_b128 v[148:151], v249
	ds_read_b128 v[140:143], v249 offset:16
	v_lshl_add_u64 v[236:237], v[202:203], 2, s[6:7]
	v_lshl_add_u32 v236, v202, 2, v246
	v_mov_b32_e32 v251, 0
	s_andn2_b64 vcc, exec, s[38:39]
	v_lshl_add_u64 v[238:239], v[202:203], 1, s[16:17]
	v_lshl_add_u64 v[238:239], v[204:205], 0, v[238:239]
	s_waitcnt vmcnt(0) lgkmcnt(0)
	v_pk_fma_f32 v[128:129], v[128:129], v[140:141], v[194:195]
	v_cndmask_b32_e64 v194, 0, 1, s[38:39]
	v_pk_fma_f32 v[134:135], v[134:135], v[150:151], v[200:201]
	v_pk_fma_f32 v[132:133], v[132:133], v[148:149], v[198:199]
	v_pk_fma_f32 v[130:131], v[130:131], v[142:143], v[196:197]
	v_cmp_ne_u32_e64 s[46:47], 1, v194
	ds_write_b128 v208, v[132:135]
	ds_write_b128 v208, v[128:131] offset:16
	ds_read_b128 v[216:219], v210
	ds_read_b128 v[220:223], v210 offset:64
	s_waitcnt lgkmcnt(0)
	global_store_dwordx4 v236, v[216:219], s[6:7]
	global_store_dwordx4 v236, v[220:223], s[6:7] offset:64
	s_cbranch_vccnz .LBB0_325
	v_mov_b32_e32 v196, v133
	v_mov_b32_e32 v197, v129
	v_mov_b32_e32 v194, v132
	v_mov_b32_e32 v195, v128
	v_pk_mul_f32 v[196:197], v[196:197], v[196:197]
	v_mov_b32_e32 v198, v135
	v_mov_b32_e32 v199, v131
	v_pk_fma_f32 v[194:195], v[194:195], v[194:195], v[196:197]
	v_mov_b32_e32 v196, v134
	v_mov_b32_e32 v197, v130
	v_pk_mul_f32 v[198:199], v[198:199], v[198:199]
	s_nop 0
	v_pk_fma_f32 v[196:197], v[196:197], v[196:197], v[198:199]
	s_nop 0
	v_pk_add_f32 v[194:195], v[194:195], v[196:197]
	s_nop 0
	v_add_f32_e32 v251, v194, v195
	ds_read_b128 v[194:197], v192
	ds_read_b128 v[198:201], v192 offset:16
	s_waitcnt lgkmcnt(1)
	v_pk_mul_f32 v[134:135], v[134:135], v[196:197]
	v_pk_mul_f32 v[132:133], v[132:133], v[194:195]
	s_waitcnt lgkmcnt(0)
	v_pk_mul_f32 v[194:195], v[130:131], v[200:201]
	v_pk_mul_f32 v[130:131], v[128:129], v[198:199]
	v_cvt_pk_bf16_f32 v128, v132, v133
	v_cvt_pk_bf16_f32 v129, v134, v135
	v_cvt_pk_bf16_f32 v130, v130, v131
	v_cvt_pk_bf16_f32 v131, v194, v195
	ds_bpermute_b32 v128, v206, v128
	ds_bpermute_b32 v129, v206, v129
	ds_bpermute_b32 v130, v206, v130
	ds_bpermute_b32 v131, v206, v131
	s_waitcnt lgkmcnt(0)
	global_store_dwordx4 v[238:239], v[128:131], off
.LBB0_325:
	ds_read_b128 v[132:135], v249 offset:512
	ds_read_b128 v[128:131], v249 offset:528
	s_lshl_b32 s76, s76, 2
	v_cmp_eq_u32_e64 s[44:45], 0, v250
	s_ashr_i32 s77, s76, 31
	s_waitcnt lgkmcnt(1)
	v_pk_fma_f32 v[126:127], v[126:127], v[134:135], v[190:191]
	v_pk_fma_f32 v[124:125], v[124:125], v[132:133], v[188:189]
	s_waitcnt lgkmcnt(0)
	v_pk_fma_f32 v[122:123], v[122:123], v[130:131], v[186:187]
	v_pk_fma_f32 v[120:121], v[120:121], v[128:129], v[184:185]
	s_and_b64 vcc, exec, s[46:47]
	ds_write_b128 v208, v[124:127]
	ds_write_b128 v208, v[120:123] offset:16
	ds_read_b128 v[216:219], v210
	ds_read_b128 v[220:223], v210 offset:64
	s_waitcnt lgkmcnt(0)
	global_store_dwordx4 v236, v[216:219], s[6:7] offset:512
	global_store_dwordx4 v236, v[220:223], s[6:7] offset:576
	s_cbranch_vccnz .LBB0_329
	ds_read_b128 v[184:187], v192 offset:512
	ds_read_b128 v[188:191], v192 offset:528
	s_waitcnt lgkmcnt(1)
	v_pk_mul_f32 v[184:185], v[124:125], v[184:185]
	s_waitcnt lgkmcnt(0)
	v_pk_mul_f32 v[188:189], v[120:121], v[188:189]
	v_mul_f32_e32 v121, v121, v121
	v_mul_f32_e32 v125, v125, v125
	v_fmac_f32_e32 v121, v120, v120
	v_mul_f32_e32 v120, v123, v123
	v_pk_mul_f32 v[190:191], v[122:123], v[190:191]
	v_fmac_f32_e32 v125, v124, v124
	v_mul_f32_e32 v124, v127, v127
	v_fmac_f32_e32 v120, v122, v122
	v_and_b32_e32 v122, 64, v242
	v_fmac_f32_e32 v124, v126, v126
	v_add_f32_e32 v120, v121, v120
	v_xor_b32_e32 v121, 16, v242
	v_add_u32_e32 v122, 64, v122
	v_add_f32_e32 v124, v125, v124
	v_cmp_lt_i32_e32 vcc, v121, v122
	v_add_f32_e32 v120, v124, v120
	v_add_f32_e32 v120, v251, v120
	v_cndmask_b32_e32 v121, v242, v121, vcc
	v_lshlrev_b32_e32 v121, 2, v121
	ds_bpermute_b32 v121, v121, v120
	v_pk_mul_f32 v[186:187], v[126:127], v[186:187]
	v_cvt_pk_bf16_f32 v184, v184, v185
	v_cvt_pk_bf16_f32 v185, v186, v187
	v_cvt_pk_bf16_f32 v186, v188, v189
	s_waitcnt lgkmcnt(0)
	v_add_f32_e32 v120, v120, v121
	v_xor_b32_e32 v121, 32, v242
	v_cmp_lt_i32_e32 vcc, v121, v122
	v_cvt_pk_bf16_f32 v187, v190, v191
	ds_bpermute_b32 v184, v206, v184
	ds_bpermute_b32 v185, v206, v185
	ds_bpermute_b32 v186, v206, v186
	ds_bpermute_b32 v187, v206, v187
	s_waitcnt lgkmcnt(0)
	global_store_dwordx4 v[238:239], v[184:187], off offset:256
	v_cndmask_b32_e32 v121, v242, v121, vcc
	v_lshlrev_b32_e32 v121, 2, v121
	ds_bpermute_b32 v121, v121, v120
	s_and_saveexec_b64 s[54:55], s[44:45]
	s_cbranch_execz .LBB0_328
	v_lshlrev_b64 v[122:123], 6, v[226:227]
	v_lshl_add_u64 v[122:123], s[20:21], 0, v[122:123]
	v_lshl_add_u64 v[122:123], s[76:77], 2, v[122:123]
	s_lshl_b32 s92, s91, 2
	v_lshl_add_u64 v[122:123], v[122:123], 0, s[92:93]
	s_waitcnt lgkmcnt(0)
	v_add_f32_e32 v120, v120, v121
	global_store_dword v[122:123], v120, off

; #define LAS __attribute__((address_space(3)))
; __device__ __forceinline__ unsigned cvt_pk_bf16(float lo, float hi) { const cvt_f32x2_t v = {lo, hi}; const cvt_bf16x2_t b = __builtin_convertvector(v, cvt_bf16x2_t); return __builtin_bit_cast(unsigned, b); }
; __device__ __forceinline__ float sq4(f32x4 v) { return (v[0] * v[0] + v[1] * v[1]) + (v[2] * v[2] + v[3] * v[3]); }
;     __device__ __forceinline__ void operator()(const f32x4 (&acc)[2][2][4][2], const Unit& u, int wr, int wc, int fr, int fq) const {
;     ...
; #pragma unroll
;         for (int ai = 0; ai < 2; ++ai) {
;             f32x4 xr[4][2][2];
; #pragma unroll
;             for (int m = 0; m < 4; ++m) { const size_t off = (size_t)(u.pm * 256 + ai * 128 + wr * 64 + m * 16 + fr) * DM + col0;
; #pragma unroll
;                 for (int bj = 0; bj < 2; ++bj)
; #pragma unroll
;                     for (int n = 0; n < 2; ++n) xr[m][bj][n] = *(const f32x4*)(xin + off + 128 * bj + 4 * n); }
;             asm volatile("" ::: "memory");
; #pragma unroll
;             for (int m = 0; m < 4; ++m) {
;                 const int row = u.pm * 256 + ai * 128 + wr * 64 + m * 16 + fr;
;                 const size_t off = (size_t)row * DM + col0;
;                 float ss = 0.f;
; #pragma unroll
;                 for (int bj = 0; bj < 2; ++bj) {
;                     const f32x4 xo0 = xr[m][bj][0] + *(const LAS f32x4*)(gtp + 128 * bj) * acc[ai][bj][m][0], xo1 = xr[m][bj][1] + *(const LAS f32x4*)(gtp + 128 * bj + 4) * acc[ai][bj][m][1];
;                     *(f32x4*)(xout + off + 128 * bj) = xo0; *(f32x4*)(xout + off + 128 * bj + 4) = xo1;
;                     if (gmn) { ss += sq4(xo0) + sq4(xo1); const f32x4 a = xo0 * *(const LAS f32x4*)(gmp + 128 * bj), c = xo1 * *(const LAS f32x4*)(gmp + 128 * bj + 4);
;                         u32x4 w; w.x = cvt_pk_bf16(a[0], a[1]); w.y = cvt_pk_bf16(a[2], a[3]); w.z = cvt_pk_bf16(c[0], c[1]); w.w = cvt_pk_bf16(c[2], c[3]); *(u32x4*)(AX + off + 128 * bj) = w; }
;                 }
;                 if (gmn) { ss += __shfl_xor(ss, 16); ss += __shfl_xor(ss, 32); if (fq == 0) statx[(size_t)row * 16 + u.pn * 4 + wc] = ss; }
;             }
.LBB0_329:
	s_waitcnt lgkmcnt(0)
	v_lshlrev_b64 v[120:121], 10, v[234:235]
	v_lshl_add_u64 v[184:185], v[120:121], 0, v[224:225]
	v_pk_fma_f32 v[120:121], v[118:119], v[150:151], v[182:183]
	v_pk_fma_f32 v[118:119], v[116:117], v[148:149], v[180:181]
	v_pk_fma_f32 v[124:125], v[110:111], v[142:143], v[178:179]
	v_pk_fma_f32 v[122:123], v[108:109], v[140:141], v[176:177]
	v_lshl_add_u64 v[126:127], v[184:185], 2, s[6:7]
	v_lshl_add_u32 v126, v184, 2, v246
	s_mov_b64 s[54:55], -1
	s_and_b64 vcc, exec, s[46:47]
	v_pk_fma_f32 v[116:117], v[100:101], v[132:133], v[172:173]
	v_pk_fma_f32 v[108:109], v[92:93], v[128:129], v[168:169]
	ds_write_b128 v208, v[118:121]
	ds_write_b128 v208, v[122:125] offset:16
	ds_read_b128 v[216:219], v210
	ds_read_b128 v[220:223], v210 offset:64
	s_waitcnt lgkmcnt(0)
	global_store_dwordx4 v126, v[216:219], s[6:7]
	global_store_dwordx4 v126, v[220:223], s[6:7] offset:64
	s_cbranch_vccnz .LBB0_333
	v_mul_f32_e32 v92, v119, v119
	v_mul_f32_e32 v93, v121, v121
	ds_read_b128 v[176:179], v192
	ds_read_b128 v[180:183], v192 offset:16
	v_fmac_f32_e32 v92, v118, v118
	v_fmac_f32_e32 v93, v120, v120
	v_add_f32_e32 v92, v92, v93
	v_mul_f32_e32 v93, v123, v123
	v_mul_f32_e32 v100, v125, v125
	v_fmac_f32_e32 v93, v122, v122
	v_fmac_f32_e32 v100, v124, v124
	v_add_f32_e32 v93, v93, v100
	v_add_f32_e32 v172, v92, v93
	s_waitcnt lgkmcnt(1)
	v_pk_mul_f32 v[92:93], v[120:121], v[178:179]
	v_pk_mul_f32 v[100:101], v[118:119], v[176:177]
	s_waitcnt lgkmcnt(0)
	v_pk_mul_f32 v[110:111], v[124:125], v[182:183]
	v_pk_mul_f32 v[120:121], v[122:123], v[180:181]
	v_cvt_pk_bf16_f32 v118, v100, v101
	v_cvt_pk_bf16_f32 v119, v92, v93
	v_cvt_pk_bf16_f32 v120, v120, v121
	v_cvt_pk_bf16_f32 v121, v110, v111
	v_lshl_add_u64 v[92:93], v[184:185], 1, s[16:17]
	ds_bpermute_b32 v118, v206, v118
	ds_bpermute_b32 v119, v206, v119
	ds_bpermute_b32 v120, v206, v120
	ds_bpermute_b32 v121, v206, v121
	s_waitcnt lgkmcnt(0)
	v_lshl_add_u64 v[92:93], v[204:205], 0, v[92:93]
	global_store_dwordx4 v[92:93], v[118:121], off
	v_pk_fma_f32 v[110:111], v[94:95], v[130:131], v[170:171]
	s_nop 0
	v_pk_fma_f32 v[118:119], v[102:103], v[134:135], v[174:175]
	ds_write_b128 v208, v[116:119]
	ds_write_b128 v208, v[108:111] offset:16
	ds_read_b128 v[216:219], v210
	ds_read_b128 v[220:223], v210 offset:64
	s_waitcnt lgkmcnt(0)
	global_store_dwordx4 v126, v[216:219], s[6:7] offset:512
	global_store_dwordx4 v126, v[220:223], s[6:7] offset:576
	ds_read_b128 v[120:123], v192 offset:512
	s_waitcnt lgkmcnt(0)
	v_pk_mul_f32 v[100:101], v[118:119], v[122:123]
	v_pk_mul_f32 v[124:125], v[116:117], v[120:121]
	ds_read_b128 v[120:123], v192 offset:528
	s_waitcnt lgkmcnt(0)
	v_pk_mul_f32 v[168:169], v[110:111], v[122:123]
	v_pk_mul_f32 v[122:123], v[108:109], v[120:121]
	v_cvt_pk_bf16_f32 v120, v124, v125
	v_cvt_pk_bf16_f32 v121, v100, v101
	v_cvt_pk_bf16_f32 v122, v122, v123
	v_cvt_pk_bf16_f32 v123, v168, v169
	ds_bpermute_b32 v120, v206, v120
	ds_bpermute_b32 v121, v206, v121
	ds_bpermute_b32 v122, v206, v122
	ds_bpermute_b32 v123, v206, v123
	s_waitcnt lgkmcnt(0)
	global_store_dwordx4 v[92:93], v[120:123], off offset:256
	v_mul_f32_e32 v92, v117, v117
	v_mul_f32_e32 v93, v119, v119
	v_fmac_f32_e32 v92, v116, v116
	v_fmac_f32_e32 v93, v118, v118
	v_add_f32_e32 v92, v92, v93
	v_mul_f32_e32 v93, v109, v109
	v_mul_f32_e32 v100, v111, v111
	v_fmac_f32_e32 v93, v108, v108
	v_fmac_f32_e32 v100, v110, v110
	v_add_f32_e32 v93, v93, v100
	v_and_b32_e32 v100, 64, v242
	v_add_f32_e32 v92, v92, v93
	v_xor_b32_e32 v93, 16, v242
	v_add_u32_e32 v100, 64, v100
	v_cmp_lt_i32_e32 vcc, v93, v100
	v_add_f32_e32 v92, v172, v92
	s_nop 0
	v_cndmask_b32_e32 v93, v242, v93, vcc
	v_lshlrev_b32_e32 v93, 2, v93
	ds_bpermute_b32 v93, v93, v92
	s_waitcnt lgkmcnt(0)
	v_add_f32_e32 v92, v92, v93
	v_xor_b32_e32 v93, 32, v242
	v_cmp_lt_i32_e32 vcc, v93, v100
	s_nop 1
	v_cndmask_b32_e32 v93, v242, v93, vcc
	v_lshlrev_b32_e32 v93, 2, v93
	ds_bpermute_b32 v93, v93, v92
	s_and_saveexec_b64 s[54:55], s[44:45]
	s_cbranch_execz .LBB0_332
	v_lshlrev_b64 v[100:101], 6, v[234:235]
	v_lshl_add_u64 v[100:101], s[20:21], 0, v[100:101]
	v_lshl_add_u64 v[100:101], s[76:77], 2, v[100:101]
	s_lshl_b32 s92, s91, 2
	v_lshl_add_u64 v[100:101], v[100:101], 0, s[92:93]
	s_waitcnt lgkmcnt(0)
	v_add_f32_e32 v92, v92, v93
	global_store_dword v[100:101], v92, off

; #define LAS __attribute__((address_space(3)))
; __device__ __forceinline__ unsigned cvt_pk_bf16(float lo, float hi) { const cvt_f32x2_t v = {lo, hi}; const cvt_bf16x2_t b = __builtin_convertvector(v, cvt_bf16x2_t); return __builtin_bit_cast(unsigned, b); }
; __device__ __forceinline__ float sq4(f32x4 v) { return (v[0] * v[0] + v[1] * v[1]) + (v[2] * v[2] + v[3] * v[3]); }
;     __device__ __forceinline__ void operator()(const f32x4 (&acc)[2][2][4][2], const Unit& u, int wr, int wc, int fr, int fq) const {
;     ...
; #pragma unroll
;         for (int ai = 0; ai < 2; ++ai) {
;             f32x4 xr[4][2][2];
; #pragma unroll
;             for (int m = 0; m < 4; ++m) { const size_t off = (size_t)(u.pm * 256 + ai * 128 + wr * 64 + m * 16 + fr) * DM + col0;
; #pragma unroll
;                 for (int bj = 0; bj < 2; ++bj)
; #pragma unroll
;                     for (int n = 0; n < 2; ++n) xr[m][bj][n] = *(const f32x4*)(xin + off + 128 * bj + 4 * n); }
;             asm volatile("" ::: "memory");
; #pragma unroll
;             for (int m = 0; m < 4; ++m) {
;                 const int row = u.pm * 256 + ai * 128 + wr * 64 + m * 16 + fr;
;                 const size_t off = (size_t)row * DM + col0;
;                 float ss = 0.f;
; #pragma unroll
;                 for (int bj = 0; bj < 2; ++bj) {
;                     const f32x4 xo0 = xr[m][bj][0] + *(const LAS f32x4*)(gtp + 128 * bj) * acc[ai][bj][m][0], xo1 = xr[m][bj][1] + *(const LAS f32x4*)(gtp + 128 * bj + 4) * acc[ai][bj][m][1];
;                     *(f32x4*)(xout + off + 128 * bj) = xo0; *(f32x4*)(xout + off + 128 * bj + 4) = xo1;
;                     if (gmn) { ss += sq4(xo0) + sq4(xo1); const f32x4 a = xo0 * *(const LAS f32x4*)(gmp + 128 * bj), c = xo1 * *(const LAS f32x4*)(gmp + 128 * bj + 4);
;                         u32x4 w; w.x = cvt_pk_bf16(a[0], a[1]); w.y = cvt_pk_bf16(a[2], a[3]); w.z = cvt_pk_bf16(c[0], c[1]); w.w = cvt_pk_bf16(c[2], c[3]); *(u32x4*)(AX + off + 128 * bj) = w; }
;                 }
;                 if (gmn) { ss += __shfl_xor(ss, 16); ss += __shfl_xor(ss, 32); if (fq == 0) statx[(size_t)row * 16 + u.pn * 4 + wc] = ss; }
;             }
.LBB0_333:
	s_andn2_b64 vcc, exec, s[54:55]
	s_cbranch_vccnz .LBB0_335
	v_pk_fma_f32 v[118:119], v[102:103], v[134:135], v[174:175]
	v_pk_fma_f32 v[110:111], v[94:95], v[130:131], v[170:171]
	ds_write_b128 v208, v[116:119]
	ds_write_b128 v208, v[108:111] offset:16
	ds_read_b128 v[216:219], v210
	ds_read_b128 v[220:223], v210 offset:64
	s_waitcnt lgkmcnt(0)
	global_store_dwordx4 v126, v[216:219], s[6:7] offset:512
	global_store_dwordx4 v126, v[220:223], s[6:7] offset:576
.LBB0_335:
	s_waitcnt lgkmcnt(0)
	v_lshlrev_b64 v[92:93], 10, v[232:233]
	v_lshl_add_u64 v[94:95], v[92:93], 0, v[224:225]
	v_pk_fma_f32 v[98:99], v[98:99], v[150:151], v[166:167]
	v_pk_fma_f32 v[96:97], v[96:97], v[148:149], v[164:165]
	v_pk_fma_f32 v[102:103], v[90:91], v[142:143], v[162:163]
	v_pk_fma_f32 v[100:101], v[88:89], v[140:141], v[160:161]
	v_lshl_add_u64 v[108:109], v[94:95], 2, s[6:7]
	v_lshl_add_u32 v108, v94, 2, v246
	s_mov_b64 s[54:55], -1
	s_and_b64 vcc, exec, s[46:47]
	v_pk_fma_f32 v[92:93], v[84:85], v[132:133], v[156:157]
	v_pk_fma_f32 v[88:89], v[76:77], v[128:129], v[152:153]
	ds_write_b128 v208, v[96:99]
	ds_write_b128 v208, v[100:103] offset:16
	ds_read_b128 v[216:219], v210
	ds_read_b128 v[220:223], v210 offset:64
	s_waitcnt lgkmcnt(0)
	global_store_dwordx4 v108, v[216:219], s[6:7]
	global_store_dwordx4 v108, v[220:223], s[6:7] offset:64
	s_cbranch_vccnz .LBB0_339
	v_mul_f32_e32 v76, v97, v97
	v_mul_f32_e32 v77, v99, v99
	ds_read_b128 v[116:119], v192
	ds_read_b128 v[120:123], v192 offset:16
	v_fmac_f32_e32 v76, v96, v96
	v_fmac_f32_e32 v77, v98, v98
	v_add_f32_e32 v76, v76, v77
	v_mul_f32_e32 v77, v101, v101
	v_mul_f32_e32 v84, v103, v103
	v_fmac_f32_e32 v77, v100, v100
	v_fmac_f32_e32 v84, v102, v102
	v_add_f32_e32 v77, v77, v84
	v_add_f32_e32 v110, v76, v77
	s_waitcnt lgkmcnt(1)
	v_pk_mul_f32 v[76:77], v[98:99], v[118:119]
	v_pk_mul_f32 v[84:85], v[96:97], v[116:117]
	s_waitcnt lgkmcnt(0)
	v_pk_mul_f32 v[90:91], v[102:103], v[122:123]
	v_pk_mul_f32 v[98:99], v[100:101], v[120:121]
	v_cvt_pk_bf16_f32 v96, v84, v85
	v_cvt_pk_bf16_f32 v97, v76, v77
	v_cvt_pk_bf16_f32 v98, v98, v99
	v_cvt_pk_bf16_f32 v99, v90, v91
	v_lshl_add_u64 v[76:77], v[94:95], 1, s[16:17]
	v_lshl_add_u64 v[76:77], v[204:205], 0, v[76:77]
	v_pk_fma_f32 v[94:95], v[86:87], v[134:135], v[158:159]
	ds_bpermute_b32 v96, v206, v96
	ds_bpermute_b32 v97, v206, v97
	ds_bpermute_b32 v98, v206, v98
	ds_bpermute_b32 v99, v206, v99
	s_waitcnt lgkmcnt(0)
	global_store_dwordx4 v[76:77], v[96:99], off
	v_pk_fma_f32 v[90:91], v[78:79], v[130:131], v[154:155]
	ds_write_b128 v208, v[92:95]
	ds_write_b128 v208, v[88:91] offset:16
	ds_read_b128 v[216:219], v210
	ds_read_b128 v[220:223], v210 offset:64
	s_waitcnt lgkmcnt(0)
	global_store_dwordx4 v108, v[216:219], s[6:7] offset:512
	global_store_dwordx4 v108, v[220:223], s[6:7] offset:576
	ds_read_b128 v[96:99], v192 offset:512
	s_waitcnt lgkmcnt(0)
	v_pk_mul_f32 v[84:85], v[94:95], v[98:99]
	v_pk_mul_f32 v[100:101], v[92:93], v[96:97]
	ds_read_b128 v[96:99], v192 offset:528
	s_waitcnt lgkmcnt(0)
	v_pk_mul_f32 v[102:103], v[90:91], v[98:99]
	v_pk_mul_f32 v[98:99], v[88:89], v[96:97]
	v_cvt_pk_bf16_f32 v96, v100, v101
	v_cvt_pk_bf16_f32 v97, v84, v85
	v_cvt_pk_bf16_f32 v98, v98, v99
	v_cvt_pk_bf16_f32 v99, v102, v103
	ds_bpermute_b32 v96, v206, v96
	ds_bpermute_b32 v97, v206, v97
	ds_bpermute_b32 v98, v206, v98
	ds_bpermute_b32 v99, v206, v99
	s_waitcnt lgkmcnt(0)
	global_store_dwordx4 v[76:77], v[96:99], off offset:256
	v_mul_f32_e32 v76, v93, v93
	v_mul_f32_e32 v77, v95, v95
	v_fmac_f32_e32 v76, v92, v92
	v_fmac_f32_e32 v77, v94, v94
	v_add_f32_e32 v76, v76, v77
	v_mul_f32_e32 v77, v89, v89
	v_mul_f32_e32 v84, v91, v91
	v_fmac_f32_e32 v77, v88, v88
	v_fmac_f32_e32 v84, v90, v90
	v_add_f32_e32 v77, v77, v84
	v_and_b32_e32 v84, 64, v242
	v_add_f32_e32 v76, v76, v77
	v_xor_b32_e32 v77, 16, v242
	v_add_u32_e32 v84, 64, v84
	v_cmp_lt_i32_e32 vcc, v77, v84
	v_add_f32_e32 v76, v110, v76
	s_nop 0
	v_cndmask_b32_e32 v77, v242, v77, vcc
	v_lshlrev_b32_e32 v77, 2, v77
	ds_bpermute_b32 v77, v77, v76
	s_waitcnt lgkmcnt(0)
	v_add_f32_e32 v76, v76, v77
	v_xor_b32_e32 v77, 32, v242
	v_cmp_lt_i32_e32 vcc, v77, v84
	s_nop 1
	v_cndmask_b32_e32 v77, v242, v77, vcc
	v_lshlrev_b32_e32 v77, 2, v77
	ds_bpermute_b32 v77, v77, v76
	s_and_saveexec_b64 s[54:55], s[44:45]
	s_cbranch_execz .LBB0_338
	v_lshlrev_b64 v[84:85], 6, v[232:233]
	v_lshl_add_u64 v[84:85], s[20:21], 0, v[84:85]
	v_lshl_add_u64 v[84:85], s[76:77], 2, v[84:85]
	s_lshl_b32 s92, s91, 2
	v_lshl_add_u64 v[84:85], v[84:85], 0, s[92:93]
	s_waitcnt lgkmcnt(0)
	v_add_f32_e32 v76, v76, v77
	global_store_dword v[84:85], v76, off

; #define LAS __attribute__((address_space(3)))
; __device__ __forceinline__ unsigned cvt_pk_bf16(float lo, float hi) { const cvt_f32x2_t v = {lo, hi}; const cvt_bf16x2_t b = __builtin_convertvector(v, cvt_bf16x2_t); return __builtin_bit_cast(unsigned, b); }
; __device__ __forceinline__ float sq4(f32x4 v) { return (v[0] * v[0] + v[1] * v[1]) + (v[2] * v[2] + v[3] * v[3]); }
;     __device__ __forceinline__ void operator()(const f32x4 (&acc)[2][2][4][2], const Unit& u, int wr, int wc, int fr, int fq) const {
;     ...
; #pragma unroll
;         for (int ai = 0; ai < 2; ++ai) {
;             f32x4 xr[4][2][2];
; #pragma unroll
;             for (int m = 0; m < 4; ++m) { const size_t off = (size_t)(u.pm * 256 + ai * 128 + wr * 64 + m * 16 + fr) * DM + col0;
; #pragma unroll
;                 for (int bj = 0; bj < 2; ++bj)
; #pragma unroll
;                     for (int n = 0; n < 2; ++n) xr[m][bj][n] = *(const f32x4*)(xin + off + 128 * bj + 4 * n); }
;             asm volatile("" ::: "memory");
; #pragma unroll
;             for (int m = 0; m < 4; ++m) {
;                 const int row = u.pm * 256 + ai * 128 + wr * 64 + m * 16 + fr;
;                 const size_t off = (size_t)row * DM + col0;
;                 float ss = 0.f;
; #pragma unroll
;                 for (int bj = 0; bj < 2; ++bj) {
;                     const f32x4 xo0 = xr[m][bj][0] + *(const LAS f32x4*)(gtp + 128 * bj) * acc[ai][bj][m][0], xo1 = xr[m][bj][1] + *(const LAS f32x4*)(gtp + 128 * bj + 4) * acc[ai][bj][m][1];
;                     *(f32x4*)(xout + off + 128 * bj) = xo0; *(f32x4*)(xout + off + 128 * bj + 4) = xo1;
;                     if (gmn) { ss += sq4(xo0) + sq4(xo1); const f32x4 a = xo0 * *(const LAS f32x4*)(gmp + 128 * bj), c = xo1 * *(const LAS f32x4*)(gmp + 128 * bj + 4);
;                         u32x4 w; w.x = cvt_pk_bf16(a[0], a[1]); w.y = cvt_pk_bf16(a[2], a[3]); w.z = cvt_pk_bf16(c[0], c[1]); w.w = cvt_pk_bf16(c[2], c[3]); *(u32x4*)(AX + off + 128 * bj) = w; }
;                 }
;                 if (gmn) { ss += __shfl_xor(ss, 16); ss += __shfl_xor(ss, 32); if (fq == 0) statx[(size_t)row * 16 + u.pn * 4 + wc] = ss; }
;             }
.LBB0_339:
	s_andn2_b64 vcc, exec, s[54:55]
	s_cbranch_vccnz .LBB0_341
	v_pk_fma_f32 v[94:95], v[86:87], v[134:135], v[158:159]
	v_pk_fma_f32 v[90:91], v[78:79], v[130:131], v[154:155]
	ds_write_b128 v208, v[92:95]
	ds_write_b128 v208, v[88:91] offset:16
	ds_read_b128 v[216:219], v210
	ds_read_b128 v[220:223], v210 offset:64
	s_waitcnt lgkmcnt(0)
	global_store_dwordx4 v108, v[216:219], s[6:7] offset:512
	global_store_dwordx4 v108, v[220:223], s[6:7] offset:576
.LBB0_341:
	s_waitcnt lgkmcnt(0)
	v_lshlrev_b64 v[76:77], 10, v[230:231]
	v_lshl_add_u64 v[78:79], v[76:77], 0, v[224:225]
	v_pk_fma_f32 v[82:83], v[82:83], v[150:151], v[146:147]
	v_pk_fma_f32 v[80:81], v[80:81], v[148:149], v[144:145]
	v_pk_fma_f32 v[86:87], v[74:75], v[142:143], v[138:139]
	v_pk_fma_f32 v[84:85], v[72:73], v[140:141], v[136:137]
	v_lshl_add_u64 v[88:89], v[78:79], 2, s[6:7]
	v_lshl_add_u32 v88, v78, 2, v246
	s_mov_b64 s[54:55], -1
	s_and_b64 vcc, exec, s[46:47]
	v_pk_fma_f32 v[76:77], v[68:69], v[132:133], v[112:113]
	v_pk_fma_f32 v[72:73], v[64:65], v[128:129], v[104:105]
	ds_write_b128 v208, v[80:83]
	ds_write_b128 v208, v[84:87] offset:16
	ds_read_b128 v[216:219], v210
	ds_read_b128 v[220:223], v210 offset:64
	s_waitcnt lgkmcnt(0)
	global_store_dwordx4 v88, v[216:219], s[6:7]
	global_store_dwordx4 v88, v[220:223], s[6:7] offset:64
	s_cbranch_vccnz .LBB0_345
	v_mul_f32_e32 v64, v81, v81
	v_mul_f32_e32 v65, v83, v83
	ds_read_b128 v[90:93], v192
	ds_read_b128 v[94:97], v192 offset:16
	v_fmac_f32_e32 v64, v80, v80
	v_fmac_f32_e32 v65, v82, v82
	v_add_f32_e32 v64, v64, v65
	v_mul_f32_e32 v65, v85, v85
	v_mul_f32_e32 v68, v87, v87
	v_fmac_f32_e32 v65, v84, v84
	v_fmac_f32_e32 v68, v86, v86
	v_add_f32_e32 v65, v65, v68
	v_add_f32_e32 v98, v64, v65
	s_waitcnt lgkmcnt(1)
	v_pk_mul_f32 v[64:65], v[82:83], v[92:93]
	v_pk_mul_f32 v[68:69], v[80:81], v[90:91]
	s_waitcnt lgkmcnt(0)
	v_pk_mul_f32 v[74:75], v[86:87], v[96:97]
	v_pk_mul_f32 v[82:83], v[84:85], v[94:95]
	v_cvt_pk_bf16_f32 v80, v68, v69
	v_cvt_pk_bf16_f32 v81, v64, v65
	v_cvt_pk_bf16_f32 v82, v82, v83
	v_cvt_pk_bf16_f32 v83, v74, v75
	v_lshl_add_u64 v[64:65], v[78:79], 1, s[16:17]
	v_lshl_add_u64 v[64:65], v[204:205], 0, v[64:65]
	v_pk_fma_f32 v[78:79], v[70:71], v[134:135], v[114:115]
	ds_bpermute_b32 v80, v206, v80
	ds_bpermute_b32 v81, v206, v81
	ds_bpermute_b32 v82, v206, v82
	ds_bpermute_b32 v83, v206, v83
	s_waitcnt lgkmcnt(0)
	global_store_dwordx4 v[64:65], v[80:83], off
	v_pk_fma_f32 v[74:75], v[66:67], v[130:131], v[106:107]
	ds_write_b128 v208, v[76:79]
	ds_write_b128 v208, v[72:75] offset:16
	ds_read_b128 v[216:219], v210
	ds_read_b128 v[220:223], v210 offset:64
	s_waitcnt lgkmcnt(0)
	global_store_dwordx4 v88, v[216:219], s[6:7] offset:512
	global_store_dwordx4 v88, v[220:223], s[6:7] offset:576
	ds_read_b128 v[80:83], v192 offset:512
	s_waitcnt lgkmcnt(0)
	v_pk_mul_f32 v[68:69], v[78:79], v[82:83]
	v_pk_mul_f32 v[84:85], v[76:77], v[80:81]
	ds_read_b128 v[80:83], v192 offset:528
	s_waitcnt lgkmcnt(0)
	v_pk_mul_f32 v[86:87], v[74:75], v[82:83]
	v_pk_mul_f32 v[82:83], v[72:73], v[80:81]
	v_cvt_pk_bf16_f32 v80, v84, v85
	v_cvt_pk_bf16_f32 v81, v68, v69
	v_cvt_pk_bf16_f32 v82, v82, v83
	v_cvt_pk_bf16_f32 v83, v86, v87
	ds_bpermute_b32 v80, v206, v80
	ds_bpermute_b32 v81, v206, v81
	ds_bpermute_b32 v82, v206, v82
	ds_bpermute_b32 v83, v206, v83
	s_waitcnt lgkmcnt(0)
	global_store_dwordx4 v[64:65], v[80:83], off offset:256
	v_mul_f32_e32 v64, v77, v77
	v_mul_f32_e32 v65, v79, v79
	v_fmac_f32_e32 v64, v76, v76
	v_fmac_f32_e32 v65, v78, v78
	v_add_f32_e32 v64, v64, v65
	v_mul_f32_e32 v65, v73, v73
	v_mul_f32_e32 v68, v75, v75
	v_fmac_f32_e32 v65, v72, v72
	v_fmac_f32_e32 v68, v74, v74
	v_add_f32_e32 v65, v65, v68
	v_and_b32_e32 v68, 64, v242
	v_add_f32_e32 v64, v64, v65
	v_xor_b32_e32 v65, 16, v242
	v_add_u32_e32 v68, 64, v68
	v_cmp_lt_i32_e32 vcc, v65, v68
	v_add_f32_e32 v64, v98, v64
	s_nop 0
	v_cndmask_b32_e32 v65, v242, v65, vcc
	v_lshlrev_b32_e32 v65, 2, v65
	ds_bpermute_b32 v65, v65, v64
	s_waitcnt lgkmcnt(0)
	v_add_f32_e32 v64, v64, v65
	v_xor_b32_e32 v65, 32, v242
	v_cmp_lt_i32_e32 vcc, v65, v68
	s_nop 1
	v_cndmask_b32_e32 v65, v242, v65, vcc
	v_lshlrev_b32_e32 v65, 2, v65
	ds_bpermute_b32 v65, v65, v64
	s_and_saveexec_b64 s[54:55], s[44:45]
	s_cbranch_execz .LBB0_344
	v_lshlrev_b64 v[68:69], 6, v[230:231]
	v_lshl_add_u64 v[68:69], s[20:21], 0, v[68:69]
	v_lshl_add_u64 v[68:69], s[76:77], 2, v[68:69]
	s_lshl_b32 s92, s91, 2
	v_lshl_add_u64 v[68:69], v[68:69], 0, s[92:93]
	s_waitcnt lgkmcnt(0)
	v_add_f32_e32 v64, v64, v65
	global_store_dword v[68:69], v64, off

; #define LAS __attribute__((address_space(3)))
; __device__ __forceinline__ unsigned cvt_pk_bf16(float lo, float hi) { const cvt_f32x2_t v = {lo, hi}; const cvt_bf16x2_t b = __builtin_convertvector(v, cvt_bf16x2_t); return __builtin_bit_cast(unsigned, b); }
; __device__ __forceinline__ float sq4(f32x4 v) { return (v[0] * v[0] + v[1] * v[1]) + (v[2] * v[2] + v[3] * v[3]); }
;     __device__ __forceinline__ void operator()(const f32x4 (&acc)[2][2][4][2], const Unit& u, int wr, int wc, int fr, int fq) const {
;     ...
; #pragma unroll
;         for (int ai = 0; ai < 2; ++ai) {
;             f32x4 xr[4][2][2];
; #pragma unroll
;             for (int m = 0; m < 4; ++m) { const size_t off = (size_t)(u.pm * 256 + ai * 128 + wr * 64 + m * 16 + fr) * DM + col0;
; #pragma unroll
;                 for (int bj = 0; bj < 2; ++bj)
; #pragma unroll
;                     for (int n = 0; n < 2; ++n) xr[m][bj][n] = *(const f32x4*)(xin + off + 128 * bj + 4 * n); }
;             asm volatile("" ::: "memory");
; #pragma unroll
;             for (int m = 0; m < 4; ++m) {
;                 const int row = u.pm * 256 + ai * 128 + wr * 64 + m * 16 + fr;
;                 const size_t off = (size_t)row * DM + col0;
;                 float ss = 0.f;
; #pragma unroll
;                 for (int bj = 0; bj < 2; ++bj) {
;                     const f32x4 xo0 = xr[m][bj][0] + *(const LAS f32x4*)(gtp + 128 * bj) * acc[ai][bj][m][0], xo1 = xr[m][bj][1] + *(const LAS f32x4*)(gtp + 128 * bj + 4) * acc[ai][bj][m][1];
;                     *(f32x4*)(xout + off + 128 * bj) = xo0; *(f32x4*)(xout + off + 128 * bj + 4) = xo1;
;                     if (gmn) { ss += sq4(xo0) + sq4(xo1); const f32x4 a = xo0 * *(const LAS f32x4*)(gmp + 128 * bj), c = xo1 * *(const LAS f32x4*)(gmp + 128 * bj + 4);
;                         u32x4 w; w.x = cvt_pk_bf16(a[0], a[1]); w.y = cvt_pk_bf16(a[2], a[3]); w.z = cvt_pk_bf16(c[0], c[1]); w.w = cvt_pk_bf16(c[2], c[3]); *(u32x4*)(AX + off + 128 * bj) = w; }
;                 }
;                 if (gmn) { ss += __shfl_xor(ss, 16); ss += __shfl_xor(ss, 32); if (fq == 0) statx[(size_t)row * 16 + u.pn * 4 + wc] = ss; }
;             }
.LBB0_345:
	s_andn2_b64 vcc, exec, s[54:55]
	s_cbranch_vccnz .LBB0_347
	v_pk_fma_f32 v[78:79], v[70:71], v[134:135], v[114:115]
	v_pk_fma_f32 v[74:75], v[66:67], v[130:131], v[106:107]
	ds_write_b128 v208, v[76:79]
	ds_write_b128 v208, v[72:75] offset:16
	ds_read_b128 v[216:219], v210
	ds_read_b128 v[220:223], v210 offset:64
	s_waitcnt lgkmcnt(0)
	global_store_dwordx4 v88, v[216:219], s[6:7] offset:512
	global_store_dwordx4 v88, v[220:223], s[6:7] offset:576
.LBB0_347:
	v_add_u32_e32 v134, 0x80, v226
	v_ashrrev_i32_e32 v135, 31, v134
	s_waitcnt lgkmcnt(0)
	v_lshlrev_b64 v[64:65], 12, v[134:135]
	v_add_u32_e32 v132, 0x90, v226
	v_lshl_add_u64 v[64:65], v[228:229], 0, v[64:65]
	v_ashrrev_i32_e32 v133, 31, v132
	global_load_dwordx4 v[136:139], v[64:65], off offset:16
	global_load_dwordx4 v[140:143], v[64:65], off
	global_load_dwordx4 v[120:123], v[64:65], off offset:528
	global_load_dwordx4 v[124:127], v[64:65], off offset:512
	v_lshlrev_b64 v[64:65], 12, v[132:133]
	v_add_u32_e32 v130, 0xa0, v226
	v_lshl_add_u64 v[64:65], v[228:229], 0, v[64:65]
	v_ashrrev_i32_e32 v131, 31, v130
	global_load_dwordx4 v[112:115], v[64:65], off offset:16
	global_load_dwordx4 v[116:119], v[64:65], off
	global_load_dwordx4 v[104:107], v[64:65], off offset:528
	global_load_dwordx4 v[108:111], v[64:65], off offset:512
	v_lshlrev_b64 v[64:65], 12, v[130:131]
	v_add_u32_e32 v128, 0xb0, v226
	v_lshl_add_u64 v[64:65], v[228:229], 0, v[64:65]
	v_ashrrev_i32_e32 v129, 31, v128
	global_load_dwordx4 v[96:99], v[64:65], off offset:16
	global_load_dwordx4 v[100:103], v[64:65], off
	global_load_dwordx4 v[88:91], v[64:65], off offset:528
	global_load_dwordx4 v[92:95], v[64:65], off offset:512
	v_lshlrev_b64 v[64:65], 12, v[128:129]
	v_lshl_add_u64 v[68:69], v[228:229], 0, v[64:65]
	global_load_dwordx4 v[72:75], v[68:69], off offset:16
	global_load_dwordx4 v[80:83], v[68:69], off
	global_load_dwordx4 v[64:67], v[68:69], off offset:528
	s_nop 0
	global_load_dwordx4 v[68:71], v[68:69], off offset:512
	v_lshlrev_b64 v[76:77], 10, v[134:135]
	v_lshl_add_u64 v[144:145], v[76:77], 0, v[224:225]
	ds_read_b128 v[84:87], v249
	ds_read_b128 v[76:79], v249 offset:16
	s_and_b64 vcc, exec, s[46:47]
	s_waitcnt vmcnt(15) lgkmcnt(0)
	v_pk_fma_f32 v[58:59], v[58:59], v[78:79], v[138:139]
	s_waitcnt vmcnt(14)
	v_pk_fma_f32 v[62:63], v[62:63], v[86:87], v[142:143]
	v_pk_fma_f32 v[60:61], v[60:61], v[84:85], v[140:141]
	v_pk_fma_f32 v[56:57], v[56:57], v[76:77], v[136:137]
	v_lshl_add_u64 v[136:137], v[144:145], 2, s[6:7]
	v_lshl_add_u32 v136, v144, 2, v246
	v_mov_b32_e32 v140, 0
	v_lshl_add_u64 v[138:139], v[144:145], 1, s[16:17]
	v_lshl_add_u64 v[138:139], v[204:205], 0, v[138:139]
	ds_write_b128 v208, v[60:63]
	ds_write_b128 v208, v[56:59] offset:16
	ds_read_b128 v[216:219], v210
	ds_read_b128 v[220:223], v210 offset:64
	s_waitcnt lgkmcnt(0)
	global_store_dwordx4 v136, v[216:219], s[6:7]
	global_store_dwordx4 v136, v[220:223], s[6:7] offset:64
	s_cbranch_vccnz .LBB0_349
	v_mov_b32_e32 v142, v61
	v_mov_b32_e32 v143, v57
	v_mov_b32_e32 v140, v60
	v_mov_b32_e32 v141, v56
	v_pk_mul_f32 v[142:143], v[142:143], v[142:143]
	v_mov_b32_e32 v144, v63
	v_mov_b32_e32 v145, v59
	v_pk_fma_f32 v[140:141], v[140:141], v[140:141], v[142:143]
	v_mov_b32_e32 v142, v62
	v_mov_b32_e32 v143, v58
	v_pk_mul_f32 v[144:145], v[144:145], v[144:145]
	s_nop 0
	v_pk_fma_f32 v[142:143], v[142:143], v[142:143], v[144:145]
	s_nop 0
	v_pk_add_f32 v[140:141], v[140:141], v[142:143]
	ds_read_b128 v[142:145], v192
	ds_read_b128 v[146:149], v192 offset:16
	v_add_f32_e32 v140, v140, v141
	s_waitcnt lgkmcnt(1)
	v_pk_mul_f32 v[62:63], v[62:63], v[144:145]
	v_pk_mul_f32 v[60:61], v[60:61], v[142:143]
	s_waitcnt lgkmcnt(0)
	v_pk_mul_f32 v[142:143], v[58:59], v[148:149]
	v_pk_mul_f32 v[58:59], v[56:57], v[146:147]
	v_cvt_pk_bf16_f32 v56, v60, v61
	v_cvt_pk_bf16_f32 v57, v62, v63
	v_cvt_pk_bf16_f32 v58, v58, v59
	v_cvt_pk_bf16_f32 v59, v142, v143
	ds_bpermute_b32 v56, v206, v56
	ds_bpermute_b32 v57, v206, v57
	ds_bpermute_b32 v58, v206, v58
	ds_bpermute_b32 v59, v206, v59
	s_waitcnt lgkmcnt(0)
	global_store_dwordx4 v[138:139], v[56:59], off
.LBB0_349:
	ds_read_b128 v[60:63], v249 offset:512
	ds_read_b128 v[56:59], v249 offset:528
	s_and_b64 vcc, exec, s[46:47]
	s_waitcnt vmcnt(14) lgkmcnt(1)
	v_pk_fma_f32 v[54:55], v[54:55], v[62:63], v[126:127]
	v_pk_fma_f32 v[52:53], v[52:53], v[60:61], v[124:125]
	s_waitcnt lgkmcnt(0)
	v_pk_fma_f32 v[50:51], v[50:51], v[58:59], v[122:123]
	v_pk_fma_f32 v[48:49], v[48:49], v[56:57], v[120:121]
	ds_write_b128 v208, v[52:55]
	ds_write_b128 v208, v[48:51] offset:16
	ds_read_b128 v[216:219], v210
	ds_read_b128 v[220:223], v210 offset:64
	s_waitcnt lgkmcnt(0)
	global_store_dwordx4 v136, v[216:219], s[6:7] offset:512
	global_store_dwordx4 v136, v[220:223], s[6:7] offset:576
	s_cbranch_vccnz .LBB0_353
	ds_read_b128 v[120:123], v192 offset:512
	ds_read_b128 v[124:127], v192 offset:528
	s_waitcnt lgkmcnt(1)
	v_pk_mul_f32 v[120:121], v[52:53], v[120:121]
	s_waitcnt lgkmcnt(0)
	v_pk_mul_f32 v[124:125], v[48:49], v[124:125]
	v_mul_f32_e32 v49, v49, v49
	v_mul_f32_e32 v53, v53, v53
	v_fmac_f32_e32 v49, v48, v48
	v_mul_f32_e32 v48, v51, v51
	v_pk_mul_f32 v[126:127], v[50:51], v[126:127]
	v_fmac_f32_e32 v53, v52, v52
	v_mul_f32_e32 v52, v55, v55
	v_fmac_f32_e32 v48, v50, v50
	v_and_b32_e32 v50, 64, v242
	v_fmac_f32_e32 v52, v54, v54
	v_add_f32_e32 v48, v49, v48
	v_xor_b32_e32 v49, 16, v242
	v_add_u32_e32 v50, 64, v50
	v_add_f32_e32 v52, v53, v52
	v_cmp_lt_i32_e32 vcc, v49, v50
	v_add_f32_e32 v48, v52, v48
	v_add_f32_e32 v48, v140, v48
	v_cndmask_b32_e32 v49, v242, v49, vcc
	v_lshlrev_b32_e32 v49, 2, v49
	ds_bpermute_b32 v49, v49, v48
	v_pk_mul_f32 v[122:123], v[54:55], v[122:123]
	v_cvt_pk_bf16_f32 v120, v120, v121
	v_cvt_pk_bf16_f32 v121, v122, v123
	v_cvt_pk_bf16_f32 v122, v124, v125
	s_waitcnt lgkmcnt(0)
	v_add_f32_e32 v48, v48, v49
	v_xor_b32_e32 v49, 32, v242
	v_cmp_lt_i32_e32 vcc, v49, v50
	v_cvt_pk_bf16_f32 v123, v126, v127
	ds_bpermute_b32 v120, v206, v120
	ds_bpermute_b32 v121, v206, v121
	ds_bpermute_b32 v122, v206, v122
	ds_bpermute_b32 v123, v206, v123
	s_waitcnt lgkmcnt(0)
	global_store_dwordx4 v[138:139], v[120:123], off offset:256
	v_cndmask_b32_e32 v49, v242, v49, vcc
	v_lshlrev_b32_e32 v49, 2, v49
	ds_bpermute_b32 v49, v49, v48
	s_and_saveexec_b64 s[54:55], s[44:45]
	s_cbranch_execz .LBB0_352
	v_lshlrev_b64 v[50:51], 6, v[134:135]
	v_lshl_add_u64 v[50:51], s[20:21], 0, v[50:51]
	v_lshl_add_u64 v[50:51], s[76:77], 2, v[50:51]
	s_lshl_b32 s92, s91, 2
	v_lshl_add_u64 v[50:51], v[50:51], 0, s[92:93]
	s_waitcnt lgkmcnt(0)
	v_add_f32_e32 v48, v48, v49
	global_store_dword v[50:51], v48, off

; #define LAS __attribute__((address_space(3)))
; __device__ __forceinline__ unsigned cvt_pk_bf16(float lo, float hi) { const cvt_f32x2_t v = {lo, hi}; const cvt_bf16x2_t b = __builtin_convertvector(v, cvt_bf16x2_t); return __builtin_bit_cast(unsigned, b); }
; __device__ __forceinline__ float sq4(f32x4 v) { return (v[0] * v[0] + v[1] * v[1]) + (v[2] * v[2] + v[3] * v[3]); }
;     __device__ __forceinline__ void operator()(const f32x4 (&acc)[2][2][4][2], const Unit& u, int wr, int wc, int fr, int fq) const {
;     ...
; #pragma unroll
;         for (int ai = 0; ai < 2; ++ai) {
;             f32x4 xr[4][2][2];
; #pragma unroll
;             for (int m = 0; m < 4; ++m) { const size_t off = (size_t)(u.pm * 256 + ai * 128 + wr * 64 + m * 16 + fr) * DM + col0;
; #pragma unroll
;                 for (int bj = 0; bj < 2; ++bj)
; #pragma unroll
;                     for (int n = 0; n < 2; ++n) xr[m][bj][n] = *(const f32x4*)(xin + off + 128 * bj + 4 * n); }
;             asm volatile("" ::: "memory");
; #pragma unroll
;             for (int m = 0; m < 4; ++m) {
;                 const int row = u.pm * 256 + ai * 128 + wr * 64 + m * 16 + fr;
;                 const size_t off = (size_t)row * DM + col0;
;                 float ss = 0.f;
; #pragma unroll
;                 for (int bj = 0; bj < 2; ++bj) {
;                     const f32x4 xo0 = xr[m][bj][0] + *(const LAS f32x4*)(gtp + 128 * bj) * acc[ai][bj][m][0], xo1 = xr[m][bj][1] + *(const LAS f32x4*)(gtp + 128 * bj + 4) * acc[ai][bj][m][1];
;                     *(f32x4*)(xout + off + 128 * bj) = xo0; *(f32x4*)(xout + off + 128 * bj + 4) = xo1;
;                     if (gmn) { ss += sq4(xo0) + sq4(xo1); const f32x4 a = xo0 * *(const LAS f32x4*)(gmp + 128 * bj), c = xo1 * *(const LAS f32x4*)(gmp + 128 * bj + 4);
;                         u32x4 w; w.x = cvt_pk_bf16(a[0], a[1]); w.y = cvt_pk_bf16(a[2], a[3]); w.z = cvt_pk_bf16(c[0], c[1]); w.w = cvt_pk_bf16(c[2], c[3]); *(u32x4*)(AX + off + 128 * bj) = w; }
;                 }
;                 if (gmn) { ss += __shfl_xor(ss, 16); ss += __shfl_xor(ss, 32); if (fq == 0) statx[(size_t)row * 16 + u.pn * 4 + wc] = ss; }
;             }
.LBB0_353:
	s_waitcnt lgkmcnt(0)
	v_lshlrev_b64 v[48:49], 10, v[132:133]
	v_lshl_add_u64 v[120:121], v[48:49], 0, v[224:225]
	s_waitcnt vmcnt(14)
	v_pk_fma_f32 v[48:49], v[46:47], v[86:87], v[118:119]
	v_pk_fma_f32 v[46:47], v[44:45], v[84:85], v[116:117]
	v_pk_fma_f32 v[52:53], v[42:43], v[78:79], v[114:115]
	v_pk_fma_f32 v[50:51], v[40:41], v[76:77], v[112:113]
	v_lshl_add_u64 v[54:55], v[120:121], 2, s[6:7]
	v_lshl_add_u32 v54, v120, 2, v246
	s_mov_b64 s[54:55], -1
	s_and_b64 vcc, exec, s[46:47]
	s_waitcnt vmcnt(12)
	v_pk_fma_f32 v[44:45], v[36:37], v[60:61], v[108:109]
	v_pk_fma_f32 v[40:41], v[28:29], v[56:57], v[104:105]
	ds_write_b128 v208, v[46:49]
	ds_write_b128 v208, v[50:53] offset:16
	ds_read_b128 v[216:219], v210
	ds_read_b128 v[220:223], v210 offset:64
	s_waitcnt lgkmcnt(0)
	global_store_dwordx4 v54, v[216:219], s[6:7]
	global_store_dwordx4 v54, v[220:223], s[6:7] offset:64
	s_cbranch_vccnz .LBB0_357
	v_mul_f32_e32 v28, v47, v47
	v_mul_f32_e32 v29, v49, v49
	ds_read_b128 v[112:115], v192
	ds_read_b128 v[116:119], v192 offset:16
	v_fmac_f32_e32 v28, v46, v46
	v_fmac_f32_e32 v29, v48, v48
	v_add_f32_e32 v28, v28, v29
	v_mul_f32_e32 v29, v51, v51
	v_mul_f32_e32 v36, v53, v53
	v_fmac_f32_e32 v29, v50, v50
	v_fmac_f32_e32 v36, v52, v52
	v_add_f32_e32 v29, v29, v36
	v_add_f32_e32 v108, v28, v29
	s_waitcnt lgkmcnt(1)
	v_pk_mul_f32 v[28:29], v[48:49], v[114:115]
	v_pk_mul_f32 v[36:37], v[46:47], v[112:113]
	s_waitcnt lgkmcnt(0)
	v_pk_mul_f32 v[42:43], v[52:53], v[118:119]
	v_pk_mul_f32 v[48:49], v[50:51], v[116:117]
	v_cvt_pk_bf16_f32 v46, v36, v37
	v_cvt_pk_bf16_f32 v47, v28, v29
	v_cvt_pk_bf16_f32 v48, v48, v49
	v_cvt_pk_bf16_f32 v49, v42, v43
	v_lshl_add_u64 v[28:29], v[120:121], 1, s[16:17]
	ds_bpermute_b32 v46, v206, v46
	ds_bpermute_b32 v47, v206, v47
	ds_bpermute_b32 v48, v206, v48
	ds_bpermute_b32 v49, v206, v49
	s_waitcnt lgkmcnt(0)
	v_lshl_add_u64 v[28:29], v[204:205], 0, v[28:29]
	global_store_dwordx4 v[28:29], v[46:49], off
	v_pk_fma_f32 v[42:43], v[30:31], v[58:59], v[106:107]
	s_nop 0
	v_pk_fma_f32 v[46:47], v[38:39], v[62:63], v[110:111]
	ds_write_b128 v208, v[44:47]
	ds_write_b128 v208, v[40:43] offset:16
	ds_read_b128 v[216:219], v210
	ds_read_b128 v[220:223], v210 offset:64
	s_waitcnt lgkmcnt(0)
	global_store_dwordx4 v54, v[216:219], s[6:7] offset:512
	global_store_dwordx4 v54, v[220:223], s[6:7] offset:576
	ds_read_b128 v[48:51], v192 offset:512
	s_waitcnt lgkmcnt(0)
	v_pk_mul_f32 v[36:37], v[46:47], v[50:51]
	v_pk_mul_f32 v[52:53], v[44:45], v[48:49]
	ds_read_b128 v[48:51], v192 offset:528
	s_waitcnt lgkmcnt(0)
	v_pk_mul_f32 v[104:105], v[42:43], v[50:51]
	v_pk_mul_f32 v[50:51], v[40:41], v[48:49]
	v_cvt_pk_bf16_f32 v48, v52, v53
	v_cvt_pk_bf16_f32 v49, v36, v37
	v_cvt_pk_bf16_f32 v50, v50, v51
	v_cvt_pk_bf16_f32 v51, v104, v105
	ds_bpermute_b32 v48, v206, v48
	ds_bpermute_b32 v49, v206, v49
	ds_bpermute_b32 v50, v206, v50
	ds_bpermute_b32 v51, v206, v51
	s_waitcnt lgkmcnt(0)
	global_store_dwordx4 v[28:29], v[48:51], off offset:256
	v_mul_f32_e32 v28, v45, v45
	v_mul_f32_e32 v29, v47, v47
	v_fmac_f32_e32 v28, v44, v44
	v_fmac_f32_e32 v29, v46, v46
	v_add_f32_e32 v28, v28, v29
	v_mul_f32_e32 v29, v41, v41
	v_mul_f32_e32 v36, v43, v43
	v_fmac_f32_e32 v29, v40, v40
	v_fmac_f32_e32 v36, v42, v42
	v_add_f32_e32 v29, v29, v36
	v_and_b32_e32 v36, 64, v242
	v_add_f32_e32 v28, v28, v29
	v_xor_b32_e32 v29, 16, v242
	v_add_u32_e32 v36, 64, v36
	v_cmp_lt_i32_e32 vcc, v29, v36
	v_add_f32_e32 v28, v108, v28
	s_nop 0
	v_cndmask_b32_e32 v29, v242, v29, vcc
	v_lshlrev_b32_e32 v29, 2, v29
	ds_bpermute_b32 v29, v29, v28
	s_waitcnt lgkmcnt(0)
	v_add_f32_e32 v28, v28, v29
	v_xor_b32_e32 v29, 32, v242
	v_cmp_lt_i32_e32 vcc, v29, v36
	s_nop 1
	v_cndmask_b32_e32 v29, v242, v29, vcc
	v_lshlrev_b32_e32 v29, 2, v29
	ds_bpermute_b32 v29, v29, v28
	s_and_saveexec_b64 s[54:55], s[44:45]
	s_cbranch_execz .LBB0_356
	v_lshlrev_b64 v[36:37], 6, v[132:133]
	v_lshl_add_u64 v[36:37], s[20:21], 0, v[36:37]
	v_lshl_add_u64 v[36:37], s[76:77], 2, v[36:37]
	s_lshl_b32 s92, s91, 2
	v_lshl_add_u64 v[36:37], v[36:37], 0, s[92:93]
	s_waitcnt lgkmcnt(0)
	v_add_f32_e32 v28, v28, v29
	global_store_dword v[36:37], v28, off

; #define LAS __attribute__((address_space(3)))
; __device__ __forceinline__ unsigned cvt_pk_bf16(float lo, float hi) { const cvt_f32x2_t v = {lo, hi}; const cvt_bf16x2_t b = __builtin_convertvector(v, cvt_bf16x2_t); return __builtin_bit_cast(unsigned, b); }
; __device__ __forceinline__ float sq4(f32x4 v) { return (v[0] * v[0] + v[1] * v[1]) + (v[2] * v[2] + v[3] * v[3]); }
;     __device__ __forceinline__ void operator()(const f32x4 (&acc)[2][2][4][2], const Unit& u, int wr, int wc, int fr, int fq) const {
;     ...
; #pragma unroll
;         for (int ai = 0; ai < 2; ++ai) {
;             f32x4 xr[4][2][2];
; #pragma unroll
;             for (int m = 0; m < 4; ++m) { const size_t off = (size_t)(u.pm * 256 + ai * 128 + wr * 64 + m * 16 + fr) * DM + col0;
; #pragma unroll
;                 for (int bj = 0; bj < 2; ++bj)
; #pragma unroll
;                     for (int n = 0; n < 2; ++n) xr[m][bj][n] = *(const f32x4*)(xin + off + 128 * bj + 4 * n); }
;             asm volatile("" ::: "memory");
; #pragma unroll
;             for (int m = 0; m < 4; ++m) {
;                 const int row = u.pm * 256 + ai * 128 + wr * 64 + m * 16 + fr;
;                 const size_t off = (size_t)row * DM + col0;
;                 float ss = 0.f;
; #pragma unroll
;                 for (int bj = 0; bj < 2; ++bj) {
;                     const f32x4 xo0 = xr[m][bj][0] + *(const LAS f32x4*)(gtp + 128 * bj) * acc[ai][bj][m][0], xo1 = xr[m][bj][1] + *(const LAS f32x4*)(gtp + 128 * bj + 4) * acc[ai][bj][m][1];
;                     *(f32x4*)(xout + off + 128 * bj) = xo0; *(f32x4*)(xout + off + 128 * bj + 4) = xo1;
;                     if (gmn) { ss += sq4(xo0) + sq4(xo1); const f32x4 a = xo0 * *(const LAS f32x4*)(gmp + 128 * bj), c = xo1 * *(const LAS f32x4*)(gmp + 128 * bj + 4);
;                         u32x4 w; w.x = cvt_pk_bf16(a[0], a[1]); w.y = cvt_pk_bf16(a[2], a[3]); w.z = cvt_pk_bf16(c[0], c[1]); w.w = cvt_pk_bf16(c[2], c[3]); *(u32x4*)(AX + off + 128 * bj) = w; }
;                 }
;                 if (gmn) { ss += __shfl_xor(ss, 16); ss += __shfl_xor(ss, 32); if (fq == 0) statx[(size_t)row * 16 + u.pn * 4 + wc] = ss; }
;             }
.LBB0_357:
	s_andn2_b64 vcc, exec, s[54:55]
	s_cbranch_vccnz .LBB0_359
	v_pk_fma_f32 v[46:47], v[38:39], v[62:63], v[110:111]
	v_pk_fma_f32 v[42:43], v[30:31], v[58:59], v[106:107]
	ds_write_b128 v208, v[44:47]
	ds_write_b128 v208, v[40:43] offset:16
	ds_read_b128 v[216:219], v210
	ds_read_b128 v[220:223], v210 offset:64
	s_waitcnt lgkmcnt(0)
	global_store_dwordx4 v54, v[216:219], s[6:7] offset:512
	global_store_dwordx4 v54, v[220:223], s[6:7] offset:576
.LBB0_359:
	s_waitcnt lgkmcnt(0)
	v_lshlrev_b64 v[28:29], 10, v[130:131]
	v_lshl_add_u64 v[30:31], v[28:29], 0, v[224:225]
	s_waitcnt vmcnt(12)
	v_pk_fma_f32 v[34:35], v[34:35], v[86:87], v[102:103]
	v_pk_fma_f32 v[32:33], v[32:33], v[84:85], v[100:101]
	v_pk_fma_f32 v[38:39], v[26:27], v[78:79], v[98:99]
	v_pk_fma_f32 v[36:37], v[24:25], v[76:77], v[96:97]
	v_lshl_add_u64 v[40:41], v[30:31], 2, s[6:7]
	v_lshl_add_u32 v40, v30, 2, v246
	s_mov_b64 s[54:55], -1
	s_and_b64 vcc, exec, s[46:47]
	s_waitcnt vmcnt(10)
	v_pk_fma_f32 v[28:29], v[20:21], v[60:61], v[92:93]
	v_pk_fma_f32 v[24:25], v[12:13], v[56:57], v[88:89]
	ds_write_b128 v208, v[32:35]
	ds_write_b128 v208, v[36:39] offset:16
	ds_read_b128 v[216:219], v210
	ds_read_b128 v[220:223], v210 offset:64
	s_waitcnt lgkmcnt(0)
	global_store_dwordx4 v40, v[216:219], s[6:7]
	global_store_dwordx4 v40, v[220:223], s[6:7] offset:64
	s_cbranch_vccnz .LBB0_363
	v_mul_f32_e32 v12, v33, v33
	v_mul_f32_e32 v13, v35, v35
	ds_read_b128 v[42:45], v192
	ds_read_b128 v[46:49], v192 offset:16
	v_fmac_f32_e32 v12, v32, v32
	v_fmac_f32_e32 v13, v34, v34
	v_add_f32_e32 v12, v12, v13
	v_mul_f32_e32 v13, v37, v37
	v_mul_f32_e32 v20, v39, v39
	v_fmac_f32_e32 v13, v36, v36
	v_fmac_f32_e32 v20, v38, v38
	v_add_f32_e32 v13, v13, v20
	v_add_f32_e32 v50, v12, v13
	s_waitcnt lgkmcnt(1)
	v_pk_mul_f32 v[12:13], v[34:35], v[44:45]
	v_pk_mul_f32 v[20:21], v[32:33], v[42:43]
	s_waitcnt lgkmcnt(0)
	v_pk_mul_f32 v[26:27], v[38:39], v[48:49]
	v_pk_mul_f32 v[34:35], v[36:37], v[46:47]
	v_cvt_pk_bf16_f32 v32, v20, v21
	v_cvt_pk_bf16_f32 v33, v12, v13
	v_cvt_pk_bf16_f32 v34, v34, v35
	v_cvt_pk_bf16_f32 v35, v26, v27
	v_lshl_add_u64 v[12:13], v[30:31], 1, s[16:17]
	v_lshl_add_u64 v[12:13], v[204:205], 0, v[12:13]
	v_pk_fma_f32 v[30:31], v[22:23], v[62:63], v[94:95]
	ds_bpermute_b32 v32, v206, v32
	ds_bpermute_b32 v33, v206, v33
	ds_bpermute_b32 v34, v206, v34
	ds_bpermute_b32 v35, v206, v35
	s_waitcnt lgkmcnt(0)
	global_store_dwordx4 v[12:13], v[32:35], off
	v_pk_fma_f32 v[26:27], v[14:15], v[58:59], v[90:91]
	ds_write_b128 v208, v[28:31]
	ds_write_b128 v208, v[24:27] offset:16
	ds_read_b128 v[216:219], v210
	ds_read_b128 v[220:223], v210 offset:64
	s_waitcnt lgkmcnt(0)
	global_store_dwordx4 v40, v[216:219], s[6:7] offset:512
	global_store_dwordx4 v40, v[220:223], s[6:7] offset:576
	ds_read_b128 v[32:35], v192 offset:512
	s_waitcnt lgkmcnt(0)
	v_pk_mul_f32 v[20:21], v[30:31], v[34:35]
	v_pk_mul_f32 v[36:37], v[28:29], v[32:33]
	ds_read_b128 v[32:35], v192 offset:528
	s_waitcnt lgkmcnt(0)
	v_pk_mul_f32 v[38:39], v[26:27], v[34:35]
	v_pk_mul_f32 v[34:35], v[24:25], v[32:33]
	v_cvt_pk_bf16_f32 v32, v36, v37
	v_cvt_pk_bf16_f32 v33, v20, v21
	v_cvt_pk_bf16_f32 v34, v34, v35
	v_cvt_pk_bf16_f32 v35, v38, v39
	ds_bpermute_b32 v32, v206, v32
	ds_bpermute_b32 v33, v206, v33
	ds_bpermute_b32 v34, v206, v34
	ds_bpermute_b32 v35, v206, v35
	s_waitcnt lgkmcnt(0)
	global_store_dwordx4 v[12:13], v[32:35], off offset:256
	v_mul_f32_e32 v12, v29, v29
	v_mul_f32_e32 v13, v31, v31
	v_fmac_f32_e32 v12, v28, v28
	v_fmac_f32_e32 v13, v30, v30
	v_add_f32_e32 v12, v12, v13
	v_mul_f32_e32 v13, v25, v25
	v_mul_f32_e32 v20, v27, v27
	v_fmac_f32_e32 v13, v24, v24
	v_fmac_f32_e32 v20, v26, v26
	v_add_f32_e32 v13, v13, v20
	v_and_b32_e32 v20, 64, v242
	v_add_f32_e32 v12, v12, v13
	v_xor_b32_e32 v13, 16, v242
	v_add_u32_e32 v20, 64, v20
	v_cmp_lt_i32_e32 vcc, v13, v20
	v_add_f32_e32 v12, v50, v12
	s_nop 0
	v_cndmask_b32_e32 v13, v242, v13, vcc
	v_lshlrev_b32_e32 v13, 2, v13
	ds_bpermute_b32 v13, v13, v12
	s_waitcnt lgkmcnt(0)
	v_add_f32_e32 v12, v12, v13
	v_xor_b32_e32 v13, 32, v242
	v_cmp_lt_i32_e32 vcc, v13, v20
	s_nop 1
	v_cndmask_b32_e32 v13, v242, v13, vcc
	v_lshlrev_b32_e32 v13, 2, v13
	ds_bpermute_b32 v13, v13, v12
	s_and_saveexec_b64 s[54:55], s[44:45]
	s_cbranch_execz .LBB0_362
	v_lshlrev_b64 v[20:21], 6, v[130:131]
	v_lshl_add_u64 v[20:21], s[20:21], 0, v[20:21]
	v_lshl_add_u64 v[20:21], s[76:77], 2, v[20:21]
	s_lshl_b32 s92, s91, 2
	v_lshl_add_u64 v[20:21], v[20:21], 0, s[92:93]
	s_waitcnt lgkmcnt(0)
	v_add_f32_e32 v12, v12, v13
	global_store_dword v[20:21], v12, off

; #define LAS __attribute__((address_space(3)))
; __device__ __forceinline__ unsigned cvt_pk_bf16(float lo, float hi) { const cvt_f32x2_t v = {lo, hi}; const cvt_bf16x2_t b = __builtin_convertvector(v, cvt_bf16x2_t); return __builtin_bit_cast(unsigned, b); }
; __device__ __forceinline__ float sq4(f32x4 v) { return (v[0] * v[0] + v[1] * v[1]) + (v[2] * v[2] + v[3] * v[3]); }
;     __device__ __forceinline__ void operator()(const f32x4 (&acc)[2][2][4][2], const Unit& u, int wr, int wc, int fr, int fq) const {
;     ...
; #pragma unroll
;         for (int ai = 0; ai < 2; ++ai) {
;             f32x4 xr[4][2][2];
; #pragma unroll
;             for (int m = 0; m < 4; ++m) { const size_t off = (size_t)(u.pm * 256 + ai * 128 + wr * 64 + m * 16 + fr) * DM + col0;
; #pragma unroll
;                 for (int bj = 0; bj < 2; ++bj)
; #pragma unroll
;                     for (int n = 0; n < 2; ++n) xr[m][bj][n] = *(const f32x4*)(xin + off + 128 * bj + 4 * n); }
;             asm volatile("" ::: "memory");
; #pragma unroll
;             for (int m = 0; m < 4; ++m) {
;                 const int row = u.pm * 256 + ai * 128 + wr * 64 + m * 16 + fr;
;                 const size_t off = (size_t)row * DM + col0;
;                 float ss = 0.f;
; #pragma unroll
;                 for (int bj = 0; bj < 2; ++bj) {
;                     const f32x4 xo0 = xr[m][bj][0] + *(const LAS f32x4*)(gtp + 128 * bj) * acc[ai][bj][m][0], xo1 = xr[m][bj][1] + *(const LAS f32x4*)(gtp + 128 * bj + 4) * acc[ai][bj][m][1];
;                     *(f32x4*)(xout + off + 128 * bj) = xo0; *(f32x4*)(xout + off + 128 * bj + 4) = xo1;
;                     if (gmn) { ss += sq4(xo0) + sq4(xo1); const f32x4 a = xo0 * *(const LAS f32x4*)(gmp + 128 * bj), c = xo1 * *(const LAS f32x4*)(gmp + 128 * bj + 4);
;                         u32x4 w; w.x = cvt_pk_bf16(a[0], a[1]); w.y = cvt_pk_bf16(a[2], a[3]); w.z = cvt_pk_bf16(c[0], c[1]); w.w = cvt_pk_bf16(c[2], c[3]); *(u32x4*)(AX + off + 128 * bj) = w; }
;                 }
;                 if (gmn) { ss += __shfl_xor(ss, 16); ss += __shfl_xor(ss, 32); if (fq == 0) statx[(size_t)row * 16 + u.pn * 4 + wc] = ss; }
;             }
.LBB0_363:
	s_andn2_b64 vcc, exec, s[54:55]
	s_cbranch_vccnz .LBB0_365
	v_pk_fma_f32 v[30:31], v[22:23], v[62:63], v[94:95]
	v_pk_fma_f32 v[26:27], v[14:15], v[58:59], v[90:91]
	ds_write_b128 v208, v[28:31]
	ds_write_b128 v208, v[24:27] offset:16
	ds_read_b128 v[216:219], v210
	ds_read_b128 v[220:223], v210 offset:64
	s_waitcnt lgkmcnt(0)
	global_store_dwordx4 v40, v[216:219], s[6:7] offset:512
	global_store_dwordx4 v40, v[220:223], s[6:7] offset:576
.LBB0_365:
	s_waitcnt lgkmcnt(0)
	v_lshlrev_b64 v[12:13], 10, v[128:129]
	v_lshl_add_u64 v[14:15], v[12:13], 0, v[224:225]
	s_waitcnt vmcnt(10)
	v_pk_fma_f32 v[18:19], v[18:19], v[86:87], v[82:83]
	v_pk_fma_f32 v[16:17], v[16:17], v[84:85], v[80:81]
	v_pk_fma_f32 v[22:23], v[10:11], v[78:79], v[74:75]
	v_pk_fma_f32 v[20:21], v[8:9], v[76:77], v[72:73]
	v_lshl_add_u64 v[24:25], v[14:15], 2, s[6:7]
	v_lshl_add_u32 v24, v14, 2, v246
	s_mov_b64 s[54:55], -1
	s_and_b64 vcc, exec, s[46:47]
	s_waitcnt vmcnt(8)
	v_pk_fma_f32 v[12:13], v[4:5], v[60:61], v[68:69]
	v_pk_fma_f32 v[8:9], v[0:1], v[56:57], v[64:65]
	ds_write_b128 v208, v[16:19]
	ds_write_b128 v208, v[20:23] offset:16
	ds_read_b128 v[216:219], v210
	ds_read_b128 v[220:223], v210 offset:64
	s_waitcnt lgkmcnt(0)
	global_store_dwordx4 v24, v[216:219], s[6:7]
	global_store_dwordx4 v24, v[220:223], s[6:7] offset:64
	s_cbranch_vccz .LBB0_372
	s_andn2_b64 vcc, exec, s[54:55]
	s_cbranch_vccz .LBB0_375

; #define LAS __attribute__((address_space(3)))
; __device__ __forceinline__ unsigned cvt_pk_bf16(float lo, float hi) { const cvt_f32x2_t v = {lo, hi}; const cvt_bf16x2_t b = __builtin_convertvector(v, cvt_bf16x2_t); return __builtin_bit_cast(unsigned, b); }
; __device__ __forceinline__ float sq4(f32x4 v) { return (v[0] * v[0] + v[1] * v[1]) + (v[2] * v[2] + v[3] * v[3]); }
;     __device__ __forceinline__ void operator()(const f32x4 (&acc)[2][2][4][2], const Unit& u, int wr, int wc, int fr, int fq) const {
;     ...
;                 for (int bj = 0; bj < 2; ++bj) {
;                     const f32x4 xo0 = xr[m][bj][0] + *(const LAS f32x4*)(gtp + 128 * bj) * acc[ai][bj][m][0], xo1 = xr[m][bj][1] + *(const LAS f32x4*)(gtp + 128 * bj + 4) * acc[ai][bj][m][1];
;                     *(f32x4*)(xout + off + 128 * bj) = xo0; *(f32x4*)(xout + off + 128 * bj + 4) = xo1;
;                     if (gmn) { ss += sq4(xo0) + sq4(xo1); const f32x4 a = xo0 * *(const LAS f32x4*)(gmp + 128 * bj), c = xo1 * *(const LAS f32x4*)(gmp + 128 * bj + 4);
;                         u32x4 w; w.x = cvt_pk_bf16(a[0], a[1]); w.y = cvt_pk_bf16(a[2], a[3]); w.z = cvt_pk_bf16(c[0], c[1]); w.w = cvt_pk_bf16(c[2], c[3]); *(u32x4*)(AX + off + 128 * bj) = w; }
;                 }
;                 if (gmn) { ss += __shfl_xor(ss, 16); ss += __shfl_xor(ss, 32); if (fq == 0) statx[(size_t)row * 16 + u.pn * 4 + wc] = ss; }
.LBB0_372:
	v_mul_f32_e32 v0, v17, v17
	v_mul_f32_e32 v1, v19, v19
	ds_read_b128 v[26:29], v192
	ds_read_b128 v[30:33], v192 offset:16
	v_fmac_f32_e32 v0, v16, v16
	v_fmac_f32_e32 v1, v18, v18
	v_add_f32_e32 v0, v0, v1
	v_mul_f32_e32 v1, v21, v21
	v_mul_f32_e32 v4, v23, v23
	v_fmac_f32_e32 v1, v20, v20
	v_fmac_f32_e32 v4, v22, v22
	v_add_f32_e32 v1, v1, v4
	v_add_f32_e32 v34, v0, v1
	s_waitcnt lgkmcnt(1)
	v_pk_mul_f32 v[0:1], v[18:19], v[28:29]
	v_pk_mul_f32 v[4:5], v[16:17], v[26:27]
	s_waitcnt lgkmcnt(0)
	v_pk_mul_f32 v[10:11], v[22:23], v[32:33]
	v_pk_mul_f32 v[18:19], v[20:21], v[30:31]
	v_cvt_pk_bf16_f32 v16, v4, v5
	v_cvt_pk_bf16_f32 v17, v0, v1
	v_cvt_pk_bf16_f32 v18, v18, v19
	v_cvt_pk_bf16_f32 v19, v10, v11
	v_lshl_add_u64 v[0:1], v[14:15], 1, s[16:17]
	v_lshl_add_u64 v[0:1], v[204:205], 0, v[0:1]
	v_pk_fma_f32 v[14:15], v[6:7], v[62:63], v[70:71]
	ds_bpermute_b32 v16, v206, v16
	ds_bpermute_b32 v17, v206, v17
	ds_bpermute_b32 v18, v206, v18
	ds_bpermute_b32 v19, v206, v19
	s_waitcnt lgkmcnt(0)
	global_store_dwordx4 v[0:1], v[16:19], off
	v_pk_fma_f32 v[10:11], v[2:3], v[58:59], v[66:67]
	ds_write_b128 v208, v[12:15]
	ds_write_b128 v208, v[8:11] offset:16
	ds_read_b128 v[216:219], v210
	ds_read_b128 v[220:223], v210 offset:64
	s_waitcnt lgkmcnt(0)
	global_store_dwordx4 v24, v[216:219], s[6:7] offset:512
	global_store_dwordx4 v24, v[220:223], s[6:7] offset:576
	ds_read_b128 v[16:19], v192 offset:512
	s_waitcnt lgkmcnt(0)
	v_pk_mul_f32 v[4:5], v[14:15], v[18:19]
	v_pk_mul_f32 v[20:21], v[12:13], v[16:17]
	ds_read_b128 v[16:19], v192 offset:528
	s_waitcnt lgkmcnt(0)
	v_pk_mul_f32 v[22:23], v[10:11], v[18:19]
	v_pk_mul_f32 v[18:19], v[8:9], v[16:17]
	v_cvt_pk_bf16_f32 v16, v20, v21
	v_cvt_pk_bf16_f32 v17, v4, v5
	v_cvt_pk_bf16_f32 v18, v18, v19
	v_cvt_pk_bf16_f32 v19, v22, v23
	ds_bpermute_b32 v16, v206, v16
	ds_bpermute_b32 v17, v206, v17
	ds_bpermute_b32 v18, v206, v18
	ds_bpermute_b32 v19, v206, v19
	s_waitcnt lgkmcnt(0)
	global_store_dwordx4 v[0:1], v[16:19], off offset:256
	v_mul_f32_e32 v0, v13, v13
	v_mul_f32_e32 v1, v15, v15
	v_fmac_f32_e32 v0, v12, v12
	v_fmac_f32_e32 v1, v14, v14
	v_add_f32_e32 v0, v0, v1
	v_mul_f32_e32 v1, v9, v9
	v_mul_f32_e32 v4, v11, v11
	v_fmac_f32_e32 v1, v8, v8
	v_fmac_f32_e32 v4, v10, v10
	v_add_f32_e32 v1, v1, v4
	v_and_b32_e32 v4, 64, v242
	v_add_f32_e32 v0, v0, v1
	v_xor_b32_e32 v1, 16, v242
	v_add_u32_e32 v4, 64, v4
	v_cmp_lt_i32_e32 vcc, v1, v4
	v_add_f32_e32 v0, v34, v0
	s_nop 0
	v_cndmask_b32_e32 v1, v242, v1, vcc
	v_lshlrev_b32_e32 v1, 2, v1
	ds_bpermute_b32 v1, v1, v0
	s_waitcnt lgkmcnt(0)
	v_add_f32_e32 v0, v0, v1
	v_xor_b32_e32 v1, 32, v242
	v_cmp_lt_i32_e32 vcc, v1, v4
	s_nop 1
	v_cndmask_b32_e32 v1, v242, v1, vcc
	v_lshlrev_b32_e32 v1, 2, v1
	ds_bpermute_b32 v1, v1, v0
	s_and_saveexec_b64 s[46:47], s[44:45]
	s_cbranch_execz .LBB0_374
	v_lshlrev_b64 v[4:5], 6, v[128:129]
	v_lshl_add_u64 v[4:5], s[20:21], 0, v[4:5]
	v_lshl_add_u64 v[4:5], s[76:77], 2, v[4:5]
	s_lshl_b32 s92, s91, 2
	v_lshl_add_u64 v[4:5], v[4:5], 0, s[92:93]
	s_waitcnt lgkmcnt(0)
	v_add_f32_e32 v0, v0, v1
	global_store_dword v[4:5], v0, off

; #define LAS __attribute__((address_space(3)))
;     __device__ __forceinline__ void operator()(const f32x4 (&acc)[2][2][4][2], const Unit& u, int wr, int wc, int fr, int fq) const {
;     ...
;                     const f32x4 xo0 = xr[m][bj][0] + *(const LAS f32x4*)(gtp + 128 * bj) * acc[ai][bj][m][0], xo1 = xr[m][bj][1] + *(const LAS f32x4*)(gtp + 128 * bj + 4) * acc[ai][bj][m][1];
;                     *(f32x4*)(xout + off + 128 * bj) = xo0; *(f32x4*)(xout + off + 128 * bj + 4) = xo1;
.LBB0_375:
	v_pk_fma_f32 v[14:15], v[6:7], v[62:63], v[70:71]
	v_pk_fma_f32 v[10:11], v[2:3], v[58:59], v[66:67]
	ds_write_b128 v208, v[12:15]
	ds_write_b128 v208, v[8:11] offset:16
	ds_read_b128 v[216:219], v210
	ds_read_b128 v[220:223], v210 offset:64
	s_waitcnt lgkmcnt(0)
	global_store_dwordx4 v24, v[216:219], s[6:7] offset:512
	global_store_dwordx4 v24, v[220:223], s[6:7] offset:576
	ds_read_b32 v216, v252
	ds_read_b32 v218, v252 offset:256
	ds_read_b32 v220, v252 offset:512
	ds_read_b32 v222, v252 offset:768
	v_mov_b32_e32 v217, v193
	v_mov_b32_e32 v219, v193
	v_mov_b32_e32 v221, v193
	v_mov_b32_e32 v223, v193
	s_waitcnt lgkmcnt(0)
	s_andn2_b64 vcc, exec, s[42:43]
	s_mov_b64 s[42:43], -1
	s_cbranch_vccnz .LBB0_308

; #define LAS __attribute__((address_space(3)))
; __global__ void __launch_bounds__(512, 2) fwd_kernel(Args args) {
;     extern __shared__ __attribute__((aligned(16))) unsigned char lds_raw[];
;     LAS unsigned char* lds = (LAS unsigned char*)lds_raw;
	.amdhsa_kernel _Z10fwd_kernel4Args
		.amdhsa_group_segment_fixed_size 16384
		.amdhsa_private_segment_fixed_size 0
		.amdhsa_kernarg_size 472
		.amdhsa_user_sgpr_count 2
		.amdhsa_user_sgpr_dispatch_ptr 0
		.amdhsa_user_sgpr_queue_ptr 0
		.amdhsa_user_sgpr_kernarg_segment_ptr 1
		.amdhsa_user_sgpr_dispatch_id 0
		.amdhsa_user_sgpr_kernarg_preload_length 0
		.amdhsa_user_sgpr_kernarg_preload_offset 0
		.amdhsa_user_sgpr_private_segment_size 0
		.amdhsa_uses_dynamic_stack 0
		.amdhsa_enable_private_segment 0
		.amdhsa_system_sgpr_workgroup_id_x 1
		.amdhsa_system_sgpr_workgroup_id_y 0
		.amdhsa_system_sgpr_workgroup_id_z 0
		.amdhsa_system_sgpr_workgroup_info 0
		.amdhsa_system_vgpr_workitem_id 2
		.amdhsa_next_free_vgpr 256
		.amdhsa_next_free_sgpr 102
		.amdhsa_accum_offset 256
		.amdhsa_reserve_vcc 1
		.amdhsa_float_round_mode_32 0
		.amdhsa_float_round_mode_16_64 0
		.amdhsa_float_denorm_mode_32 3
		.amdhsa_float_denorm_mode_16_64 3
		.amdhsa_dx10_clamp 1
		.amdhsa_ieee_mode 1
		.amdhsa_fp16_overflow 0
		.amdhsa_tg_split 0
		.amdhsa_exception_fp_ieee_invalid_op 0
		.amdhsa_exception_fp_denorm_src 0
		.amdhsa_exception_fp_ieee_div_zero 0
		.amdhsa_exception_fp_ieee_overflow 0
		.amdhsa_exception_fp_ieee_underflow 0
		.amdhsa_exception_fp_ieee_inexact 0
		.amdhsa_exception_int_div_zero 0
	.end_amdhsa_kernel

; #define LAS __attribute__((address_space(3)))
; __global__ void __launch_bounds__(512, 2) fwd_kernel(Args args) {
;     extern __shared__ __attribute__((aligned(16))) unsigned char lds_raw[];
;     LAS unsigned char* lds = (LAS unsigned char*)lds_raw;
amdhsa.kernels:
  - .agpr_count:     0
    .args:
      - .offset:         0
        .size:           216
        .value_kind:     by_value
      - .offset:         216
        .size:           4
        .value_kind:     hidden_block_count_x
      - .offset:         220
        .size:           4
        .value_kind:     hidden_block_count_y
      - .offset:         224
        .size:           4
        .value_kind:     hidden_block_count_z
      - .offset:         228
        .size:           2
        .value_kind:     hidden_group_size_x
      - .offset:         230
        .size:           2
        .value_kind:     hidden_group_size_y
      - .offset:         232
        .size:           2
        .value_kind:     hidden_group_size_z
      - .offset:         234
        .size:           2
        .value_kind:     hidden_remainder_x
      - .offset:         236
        .size:           2
        .value_kind:     hidden_remainder_y
      - .offset:         238
        .size:           2
        .value_kind:     hidden_remainder_z
      - .offset:         256
        .size:           8
        .value_kind:     hidden_global_offset_x
      - .offset:         264
        .size:           8
        .value_kind:     hidden_global_offset_y
      - .offset:         272
        .size:           8
        .value_kind:     hidden_global_offset_z
      - .offset:         280
        .size:           2
        .value_kind:     hidden_grid_dims
      - .offset:         304
        .size:           8
        .value_kind:     hidden_multigrid_sync_arg
      - .offset:         336
        .size:           4
        .value_kind:     hidden_dynamic_lds_size
    .group_segment_fixed_size: 16384
    .kernarg_segment_align: 8
    .kernarg_segment_size: 472
    .language:       OpenCL C
    .language_version:
      - 2
      - 0
    .max_flat_workgroup_size: 512
    .name:           _Z10fwd_kernel4Args
    .private_segment_fixed_size: 0
    .sgpr_count:     108
    .sgpr_spill_count: 228
    .symbol:         _Z10fwd_kernel4Args.kd
    .uniform_work_group_size: 1
    .uses_dynamic_stack: false
    .vgpr_count:     256
    .vgpr_spill_count: 0
    .wavefront_size: 64
